# v25: v11 + one static s_setprio 1 for waves 4-7 around the P7 prompt-attention item loop (reset to 0 after it)
# speedup vs baseline: 1.0047x; 1.0020x over previous
; #define LAS __attribute__((address_space(3)))
; DI void attn_prompt_item(const Params& p, int item, ldsp lds, int tid_) {
;   int tid = tid_; asm volatile("" : "+v"(tid));
;   const int wid = __builtin_amdgcn_readfirstlane(tid >> 6), lane = tid & 63, l31 = lane & 31, h2 = lane >> 5;
;   const int b = item >> 5, h = (item >> 3) & 3, qt = item & 7;
;   bf16_t* qx = (bf16_t*)(p.ws + B_QX);
;   const bf16_t* mkb = (const bf16_t*)(p.ws + B_MKB);
;   const bf16_t* mvt = (const bf16_t*)(p.ws + B_MVT);
;   const size_t qrow = (size_t)b * 2048 + qt * 256 + wid * 32 + l31;
;   bf16x8 qreg[8];
; #pragma unroll
;   for (int s = 0; s < 8; ++s) qreg[s] = *(const bf16x8*)(qx + qrow * D + h * 256 + 16 * s + 8 * h2);
; #pragma unroll
;   for (int hb = 0; hb < 2; ++hb) {
;     u32x4 kp[8];
; #pragma unroll
;     for (int i = 0; i < 8; ++i) { const int idx = tid + 512 * (hb * 8 + i), key = idx >> 5, c = idx & 31; kp[i] = ld16(mkb + (size_t)(b * 256 + key) * D + h * 256 + c * 8); }
; #pragma unroll
;     for (int i = 0; i < 8; ++i) { const int idx = tid + 512 * (hb * 8 + i), key = idx >> 5, c = idx & 31; *(LAS u32x4*)(lds + key * 512 + ((c ^ (key & 15)) * 16)) = kp[i]; }
; DI void phase_attn(const Params& p, ldsp lds, int tid) {
;   const int G = gridDim.x;
;   if (blockIdx.x & 1) for (int j = blockIdx.x; j < 512; j += G) attn_sample_item(p, j, lds, tid);
;   for (int i = blockIdx.x; i < 256; i += G) attn_prompt_item(p, i, lds, tid);
.LBB0_1670:
	s_cmpk_gt_i32 s2, 0xff
	s_cbranch_scc1 .LBB0_1673
	s_add_u32 s4, s42, 0xfb40000
	s_addc_u32 s5, s43, 0
	s_add_u32 s0, s42, 0xb140000
	s_addc_u32 s1, s43, 0
	v_mbcnt_hi_u32_b32 v168, -1, v213
	s_add_u32 s6, s42, 0xb540000
	v_and_b32_e32 v0, 64, v168
	s_addc_u32 s7, s43, 0
	s_lshl_b32 s30, s2, 5
	s_lshl_b32 s31, s94, 5
	s_lshl_b32 s33, s2, 8
	s_lshl_b32 s34, s94, 8
	s_mov_b32 s27, 0
	v_mov_b32_e32 v161, 0
	s_mov_b32 s35, 0xf149f2ca
	v_xor_b32_e32 v169, 32, v168
	v_add_u32_e32 v170, 64, v0
	v_mov_b32_e32 v171, 0xf0
	s_mov_b32 s38, 0x2100000
	s_add_i32 s39, 16, 0x10000
	s_add_i32 s40, 16, 0x14000
	s_add_i32 s41, 16, 0x18000
	s_add_i32 s44, 16, 0x1c000
	s_mov_b32 s45, s2
	v_readfirstlane_b32 s98, v212
	s_nop 3
	s_lshr_b32 s98, s98, 6
	s_cmp_ge_u32 s98, 4
	s_cbranch_scc0 .Lp7prio_done
	s_setprio 1
.Lp7prio_done:
.LBB0_1672:
	v_mov_b32_e32 v68, v212
	s_ashr_i32 s28, s45, 5
	s_ashr_i32 s29, s28, 31
	v_readfirstlane_b32 s3, v68
	s_lshl_b64 s[46:47], s[28:29], 11
	s_and_b32 s26, s33, 0x700
	s_ashr_i32 s3, s3, 1
	v_and_b32_e32 v69, 31, v68
	s_or_b32 s26, s46, s26
	s_and_b32 s48, s3, 0xffffffe0
	s_ashr_i32 s49, s48, 31
	v_or_b32_e32 v0, s26, v69
	v_mov_b32_e32 v1, s47
	s_and_b32 s3, s30, 0x300
	v_add_u32_e32 v6, 0x200, v68
	v_lshl_add_u64 v[0:1], v[0:1], 0, s[48:49]
	s_lshl_b32 s26, s3, 1
	s_lshl_b32 s29, s28, 8
	v_ashrrev_i32_e32 v176, 5, v68
	v_ashrrev_i32_e32 v177, 5, v6
	v_lshlrev_b64 v[162:163], 11, v[0:1]
	s_add_u32 s46, s0, s26
	v_lshlrev_b32_e32 v174, 4, v68
	v_add_u32_e32 v4, s29, v176
	v_add_u32_e32 v6, s29, v177
	v_bfe_u32 v208, v68, 5, 1
	v_lshl_add_u64 v[0:1], s[4:5], 0, v[162:163]
	s_addc_u32 s47, s1, 0
	v_and_b32_e32 v164, 0x1f0, v174
	v_mov_b32_e32 v165, v161
	v_ashrrev_i32_e32 v5, 31, v4
	v_ashrrev_i32_e32 v7, 31, v6
	v_lshl_add_u64 v[0:1], v[0:1], 0, s[26:27]
	v_lshlrev_b32_e32 v2, 4, v208
	v_mov_b32_e32 v3, v161
	v_lshl_add_u64 v[64:65], s[46:47], 0, v[164:165]
	v_lshlrev_b64 v[4:5], 11, v[4:5]
	v_lshlrev_b64 v[6:7], 11, v[6:7]
	v_lshl_add_u64 v[166:167], v[0:1], 0, v[2:3]
	v_lshl_add_u64 v[4:5], v[64:65], 0, v[4:5]
	v_lshl_add_u64 v[8:9], v[64:65], 0, v[6:7]
	global_load_dwordx4 v[0:3], v[166:167], off
	global_load_dwordx4 v[152:155], v[166:167], off offset:32
	global_load_dwordx4 v[148:151], v[166:167], off offset:64
	global_load_dwordx4 v[144:147], v[166:167], off offset:96
	global_load_dwordx4 v[140:143], v[166:167], off offset:128
	global_load_dwordx4 v[136:139], v[166:167], off offset:160
	global_load_dwordx4 v[132:135], v[166:167], off offset:192
	global_load_dwordx4 v[128:131], v[166:167], off offset:224
	s_nop 0
	global_load_dwordx4 v[4:7], v[4:5], off
	s_nop 0
	global_load_dwordx4 v[8:11], v[8:9], off
	v_add_u32_e32 v12, 0x400, v68
	v_add_u32_e32 v14, 0x600, v68
	v_add_u32_e32 v20, 0x800, v68
	v_add_u32_e32 v22, 0xa00, v68
	v_ashrrev_i32_e32 v178, 5, v12
	v_ashrrev_i32_e32 v180, 5, v14
	v_ashrrev_i32_e32 v181, 5, v20
	v_ashrrev_i32_e32 v183, 5, v22
	v_add_u32_e32 v28, 0xc00, v68
	v_add_u32_e32 v30, 0xe00, v68
	v_add_u32_e32 v36, 0x1000, v68
	v_add_u32_e32 v38, 0x1200, v68
	v_add_u32_e32 v44, 0x1400, v68
	v_add_u32_e32 v46, 0x1600, v68
	v_add_u32_e32 v52, 0x1800, v68
	v_add_u32_e32 v54, 0x1a00, v68
	v_add_u32_e32 v60, 0x1c00, v68
	v_add_u32_e32 v66, 0x1e00, v68
	v_add_u32_e32 v12, s29, v178
	v_add_u32_e32 v14, s29, v180
	v_add_u32_e32 v20, s29, v181
	v_add_u32_e32 v22, s29, v183
	v_ashrrev_i32_e32 v184, 5, v28
	v_ashrrev_i32_e32 v186, 5, v30
	v_ashrrev_i32_e32 v195, 5, v36
	v_ashrrev_i32_e32 v197, 5, v38
	v_ashrrev_i32_e32 v199, 5, v44
	v_ashrrev_i32_e32 v201, 5, v46
	v_ashrrev_i32_e32 v203, 5, v52
	v_ashrrev_i32_e32 v204, 5, v54
	v_ashrrev_i32_e32 v206, 5, v60
	v_ashrrev_i32_e32 v207, 5, v66
	v_ashrrev_i32_e32 v13, 31, v12
	v_ashrrev_i32_e32 v15, 31, v14
	v_ashrrev_i32_e32 v21, 31, v20
	v_ashrrev_i32_e32 v23, 31, v22
	v_add_u32_e32 v28, s29, v184
	v_add_u32_e32 v30, s29, v186
	v_add_u32_e32 v36, s29, v195
	v_add_u32_e32 v38, s29, v197
	v_add_u32_e32 v44, s29, v199
	v_add_u32_e32 v46, s29, v201
	v_add_u32_e32 v52, s29, v203
	v_add_u32_e32 v54, s29, v204
	v_add_u32_e32 v60, s29, v206
	v_add_u32_e32 v66, s29, v207
	v_lshlrev_b64 v[12:13], 11, v[12:13]
	v_lshlrev_b64 v[14:15], 11, v[14:15]
	v_lshlrev_b64 v[20:21], 11, v[20:21]
	v_lshlrev_b64 v[22:23], 11, v[22:23]
	v_ashrrev_i32_e32 v29, 31, v28
	v_ashrrev_i32_e32 v31, 31, v30
	v_ashrrev_i32_e32 v37, 31, v36
	v_ashrrev_i32_e32 v39, 31, v38
	v_ashrrev_i32_e32 v45, 31, v44
	v_ashrrev_i32_e32 v47, 31, v46
	v_ashrrev_i32_e32 v53, 31, v52
	v_ashrrev_i32_e32 v55, 31, v54
	v_ashrrev_i32_e32 v61, 31, v60
	v_ashrrev_i32_e32 v67, 31, v66
	v_lshl_add_u64 v[12:13], v[64:65], 0, v[12:13]
	v_lshl_add_u64 v[16:17], v[64:65], 0, v[14:15]
	v_lshl_add_u64 v[20:21], v[64:65], 0, v[20:21]
	v_lshl_add_u64 v[24:25], v[64:65], 0, v[22:23]
	v_lshlrev_b64 v[28:29], 11, v[28:29]
	v_lshlrev_b64 v[30:31], 11, v[30:31]
	v_lshlrev_b64 v[36:37], 11, v[36:37]
	v_lshlrev_b64 v[38:39], 11, v[38:39]
	v_lshlrev_b64 v[44:45], 11, v[44:45]
	v_lshlrev_b64 v[46:47], 11, v[46:47]
	v_lshlrev_b64 v[52:53], 11, v[52:53]
	v_lshlrev_b64 v[54:55], 11, v[54:55]
	v_lshlrev_b64 v[60:61], 11, v[60:61]
	v_lshlrev_b64 v[66:67], 11, v[66:67]
	global_load_dwordx4 v[12:15], v[12:13], off
	s_nop 0
	global_load_dwordx4 v[16:19], v[16:17], off
	s_nop 0
	global_load_dwordx4 v[20:23], v[20:21], off
	s_nop 0
	global_load_dwordx4 v[24:27], v[24:25], off
	v_lshl_add_u64 v[28:29], v[64:65], 0, v[28:29]
	v_lshl_add_u64 v[32:33], v[64:65], 0, v[30:31]
	v_lshl_add_u64 v[36:37], v[64:65], 0, v[36:37]
	v_lshl_add_u64 v[40:41], v[64:65], 0, v[38:39]
	v_lshl_add_u64 v[44:45], v[64:65], 0, v[44:45]
	v_lshl_add_u64 v[48:49], v[64:65], 0, v[46:47]
	v_lshl_add_u64 v[52:53], v[64:65], 0, v[52:53]
	v_lshl_add_u64 v[56:57], v[64:65], 0, v[54:55]
	v_lshl_add_u64 v[60:61], v[64:65], 0, v[60:61]
	v_lshl_add_u64 v[64:65], v[64:65], 0, v[66:67]
	global_load_dwordx4 v[28:31], v[28:29], off
	s_nop 0
	global_load_dwordx4 v[32:35], v[32:33], off
	s_nop 0
	global_load_dwordx4 v[36:39], v[36:37], off
	s_nop 0
	global_load_dwordx4 v[40:43], v[40:41], off
	s_nop 0
	global_load_dwordx4 v[44:47], v[44:45], off
	s_nop 0
	global_load_dwordx4 v[48:51], v[48:49], off
	s_nop 0
	global_load_dwordx4 v[52:55], v[52:53], off
	s_nop 0
	global_load_dwordx4 v[56:59], v[56:57], off
	v_bitop3_b32 v72, v176, v69, 15 bitop3:0x6c
	global_load_dwordx4 v[60:63], v[60:61], off
	v_lshlrev_b32_e32 v71, 9, v176
	global_load_dwordx4 v[64:67], v[64:65], off
	v_lshlrev_b32_e32 v72, 4, v72
	v_add3_u32 v179, 16, v71, v72
	s_waitcnt vmcnt(15)
; #define LAS __attribute__((address_space(3)))
; DI void attn_prompt_item(const Params& p, int item, ldsp lds, int tid_) {
;     ...
;     for (int i = 0; i < 8; ++i) { const int idx = tid + 512 * (hb * 8 + i), key = idx >> 5, c = idx & 31; kp[i] = ld16(mkb + (size_t)(b * 256 + key) * D + h * 256 + c * 8); }
; #pragma unroll
;     for (int i = 0; i < 8; ++i) { const int idx = tid + 512 * (hb * 8 + i), key = idx >> 5, c = idx & 31; *(LAS u32x4*)(lds + key * 512 + ((c ^ (key & 15)) * 16)) = kp[i]; }
;   }
;   __syncthreads();
;   f32x16 S[8];
; #pragma unroll
;   for (int kt = 0; kt < 8; ++kt)
; #pragma unroll
;     for (int i = 0; i < 16; ++i) S[kt][i] = 0.f;
; #pragma unroll
;   for (int sh = 0; sh < 2; ++sh) {
;     if (sh == 1) {
;       __builtin_amdgcn_sched_barrier(0);
; #pragma unroll
;       for (int s = 0; s < 8; ++s) qreg[s] = *(const bf16x8*)(qx + qrow * D + h * 256 + 16 * (8 + s) + 8 * h2);
;     }
;     {
;       bf16x8 kfa[4], kfb[4];
;     ...
; #pragma unroll
;       for (int j = 0; j < 4; ++j) kfa[j] = *(const LAS bf16x8*)KF_ADDR(0, j);
; #pragma unroll
;       for (int gi = 0; gi < 16; ++gi) {
;         if (gi + 1 < 16) {
; #pragma unroll
;           for (int j = 0; j < 4; ++j) { if (gi & 1) kfa[j] = *(const LAS bf16x8*)KF_ADDR(gi + 1, j); else kfb[j] = *(const LAS bf16x8*)KF_ADDR(gi + 1, j); } }
; #pragma unroll
;         for (int j = 0; j < 4; ++j) S[gi >> 1] = __builtin_amdgcn_mfma_f32_32x32x16_bf16((gi & 1) ? kfb[j] : kfa[j], qreg[(gi & 1) * 4 + j], S[gi >> 1], 0, 0, 0);
;         __builtin_amdgcn_sched_barrier(0);
;       }
	ds_write_b128 v179, v[4:7]
	v_bitop3_b32 v5, v177, v69, 15 bitop3:0x6c
	v_lshlrev_b32_e32 v4, 9, v177
	v_lshlrev_b32_e32 v5, 4, v5
	v_add3_u32 v182, 16, v4, v5
	v_bitop3_b32 v5, v178, v69, 15 bitop3:0x6c
	v_lshlrev_b32_e32 v4, 9, v178
	v_lshlrev_b32_e32 v5, 4, v5
	v_add3_u32 v185, 16, v4, v5
	v_bitop3_b32 v5, v180, v69, 15 bitop3:0x6c
	v_lshlrev_b32_e32 v4, 9, v180
	v_lshlrev_b32_e32 v5, 4, v5
	v_add3_u32 v187, 16, v4, v5
	v_bitop3_b32 v5, v181, v69, 15 bitop3:0x6c
	v_lshlrev_b32_e32 v4, 9, v181
	v_lshlrev_b32_e32 v5, 4, v5
	v_add3_u32 v188, 16, v4, v5
	v_bitop3_b32 v5, v183, v69, 15 bitop3:0x6c
	v_lshlrev_b32_e32 v4, 9, v183
	v_lshlrev_b32_e32 v5, 4, v5
	v_add3_u32 v189, 16, v4, v5
	v_bitop3_b32 v5, v184, v69, 15 bitop3:0x6c
	v_lshlrev_b32_e32 v4, 9, v184
	v_lshlrev_b32_e32 v5, 4, v5
	v_add3_u32 v190, 16, v4, v5
	v_bitop3_b32 v5, v186, v69, 15 bitop3:0x6c
	v_lshlrev_b32_e32 v4, 9, v186
	v_lshlrev_b32_e32 v5, 4, v5
	v_add3_u32 v191, 16, v4, v5
	v_bitop3_b32 v5, v195, v69, 15 bitop3:0x6c
	v_lshlrev_b32_e32 v4, 9, v195
	v_lshlrev_b32_e32 v5, 4, v5
	v_add3_u32 v192, 16, v4, v5
	v_bitop3_b32 v5, v197, v69, 15 bitop3:0x6c
	v_lshlrev_b32_e32 v4, 9, v197
	v_lshlrev_b32_e32 v5, 4, v5
	v_add3_u32 v193, 16, v4, v5
	v_bitop3_b32 v5, v199, v69, 15 bitop3:0x6c
	v_lshlrev_b32_e32 v4, 9, v199
	v_lshlrev_b32_e32 v5, 4, v5
	v_add3_u32 v194, 16, v4, v5
	v_bitop3_b32 v5, v201, v69, 15 bitop3:0x6c
	v_lshlrev_b32_e32 v4, 9, v201
	v_lshlrev_b32_e32 v5, 4, v5
	v_add3_u32 v196, 16, v4, v5
	v_bitop3_b32 v5, v203, v69, 15 bitop3:0x6c
	v_lshlrev_b32_e32 v4, 9, v203
	v_lshlrev_b32_e32 v5, 4, v5
	v_add3_u32 v200, 16, v4, v5
	v_bitop3_b32 v5, v204, v69, 15 bitop3:0x6c
	v_lshlrev_b32_e32 v4, 9, v204
	v_lshlrev_b32_e32 v5, 4, v5
	v_add3_u32 v198, 16, v4, v5
	v_bitop3_b32 v5, v206, v69, 15 bitop3:0x6c
	v_lshlrev_b32_e32 v4, 9, v206
	v_lshlrev_b32_e32 v5, 4, v5
	v_add3_u32 v202, 16, v4, v5
	v_bitop3_b32 v5, v207, v69, 15 bitop3:0x6c
	v_lshrrev_b32_e32 v70, 5, v68
	v_lshlrev_b32_e32 v4, 9, v207
	v_lshlrev_b32_e32 v5, 4, v5
	v_and_b32_e32 v175, 15, v68
	v_add3_u32 v205, 16, v4, v5
	v_lshlrev_b32_e32 v172, 9, v69
	v_bitop3_b32 v4, v70, v175, 1 bitop3:0x6c
	v_add_u32_e32 v173, 16, v172
	v_lshlrev_b32_e32 v209, 4, v4
	s_waitcnt vmcnt(14)
	ds_write_b128 v182, v[8:11]
	s_waitcnt vmcnt(13)
	ds_write_b128 v185, v[12:15]
	s_waitcnt vmcnt(12)
	ds_write_b128 v187, v[16:19]
	s_waitcnt vmcnt(11)
	ds_write_b128 v188, v[20:23]
	s_waitcnt vmcnt(10)
	ds_write_b128 v189, v[24:27]
	v_add_u32_e32 v24, v173, v209
	s_waitcnt vmcnt(9)
	ds_write_b128 v190, v[28:31]
	s_waitcnt vmcnt(8)
	ds_write_b128 v191, v[32:35]
	s_waitcnt vmcnt(7)
	ds_write_b128 v192, v[36:39]
	s_waitcnt vmcnt(6)
	ds_write_b128 v193, v[40:43]
	s_waitcnt vmcnt(5)
	ds_write_b128 v194, v[44:47]
	s_waitcnt vmcnt(4)
	ds_write_b128 v196, v[48:51]
	s_waitcnt vmcnt(3)
	ds_write_b128 v200, v[52:55]
	s_waitcnt vmcnt(2)
	ds_write_b128 v198, v[56:59]
	s_waitcnt vmcnt(1)
	ds_write_b128 v202, v[60:63]
	s_waitcnt vmcnt(0)
	ds_write_b128 v205, v[64:67]
	s_waitcnt lgkmcnt(0)
	s_barrier
	ds_read_b128 v[4:7], v24
	v_bitop3_b32 v8, v208, v175, 2 bitop3:0x36
	v_lshlrev_b32_e32 v210, 4, v8
	v_add_u32_e32 v25, v173, v210
	ds_read_b128 v[8:11], v25
	s_waitcnt lgkmcnt(1)
	v_mfma_f32_32x32x16_bf16 v[112:127], v[4:7], v[0:3], 0
	v_bitop3_b32 v12, v208, v175, 4 bitop3:0x36
	v_lshlrev_b32_e32 v211, 4, v12
	v_bitop3_b32 v4, v208, v175, 6 bitop3:0x36
	v_add_u32_e32 v26, v173, v211
	v_lshlrev_b32_e32 v218, 4, v4
	v_add_u32_e32 v27, v173, v218
	ds_read_b128 v[4:7], v26
	ds_read_b128 v[12:15], v27
	s_waitcnt lgkmcnt(2)
	v_mfma_f32_32x32x16_bf16 v[112:127], v[8:11], v[152:155], v[112:127]
	v_bitop3_b32 v16, v208, v175, 8 bitop3:0x36
	v_bitop3_b32 v20, v208, v175, 12 bitop3:0x36
	v_lshlrev_b32_e32 v226, 4, v16
	v_bitop3_b32 v8, v208, v175, 10 bitop3:0x36
	v_lshlrev_b32_e32 v228, 4, v20
	v_add_u32_e32 v28, v173, v226
	v_lshlrev_b32_e32 v227, 4, v8
	s_waitcnt lgkmcnt(1)
	v_mfma_f32_32x32x16_bf16 v[112:127], v[4:7], v[148:151], v[112:127]
	v_bitop3_b32 v4, v208, v175, 14 bitop3:0x36
	v_add_u32_e32 v30, v173, v228
	v_lshlrev_b32_e32 v229, 4, v4
	v_add_u32_e32 v29, v173, v227
	ds_read_b128 v[8:11], v28
	ds_read_b128 v[16:19], v29
	v_add_u32_e32 v31, v173, v229
	ds_read_b128 v[4:7], v30
	ds_read_b128 v[20:23], v31
	v_lshlrev_b32_e32 v160, 3, v208
	s_waitcnt lgkmcnt(4)
	v_mfma_f32_32x32x16_bf16 v[112:127], v[12:15], v[144:147], v[112:127]
	s_waitcnt lgkmcnt(3)
	v_mfma_f32_32x32x16_bf16 v[112:127], v[8:11], v[140:143], v[112:127]
	s_waitcnt lgkmcnt(2)
	v_mfma_f32_32x32x16_bf16 v[112:127], v[16:19], v[136:139], v[112:127]
	s_waitcnt lgkmcnt(1)
	v_mfma_f32_32x32x16_bf16 v[112:127], v[4:7], v[132:135], v[112:127]
	ds_read_b128 v[4:7], v24 offset:16384
	ds_read_b128 v[8:11], v25 offset:16384
	ds_read_b128 v[12:15], v26 offset:16384
	ds_read_b128 v[16:19], v27 offset:16384
	s_waitcnt lgkmcnt(4)
	v_mfma_f32_32x32x16_bf16 v[112:127], v[20:23], v[128:131], v[112:127]
	s_waitcnt lgkmcnt(3)
	v_mfma_f32_32x32x16_bf16 v[96:111], v[4:7], v[0:3], 0
	s_waitcnt lgkmcnt(2)
	v_mfma_f32_32x32x16_bf16 v[96:111], v[8:11], v[152:155], v[96:111]
	s_waitcnt lgkmcnt(1)
	v_mfma_f32_32x32x16_bf16 v[96:111], v[12:15], v[148:151], v[96:111]
	ds_read_b128 v[4:7], v28 offset:16384
	ds_read_b128 v[8:11], v29 offset:16384
	ds_read_b128 v[12:15], v30 offset:16384
	ds_read_b128 v[20:23], v31 offset:16384
	s_waitcnt lgkmcnt(4)
	v_mfma_f32_32x32x16_bf16 v[96:111], v[16:19], v[144:147], v[96:111]
	s_waitcnt lgkmcnt(3)
	v_mfma_f32_32x32x16_bf16 v[96:111], v[4:7], v[140:143], v[96:111]
	s_waitcnt lgkmcnt(2)
	v_mfma_f32_32x32x16_bf16 v[96:111], v[8:11], v[136:139], v[96:111]
	s_waitcnt lgkmcnt(1)
; #define LAS __attribute__((address_space(3)))
; DI void attn_prompt_item(const Params& p, int item, ldsp lds, int tid_) {
;     ...
;     {
;       bf16x8 kfa[4], kfb[4];
;     ...
; #pragma unroll
;       for (int j = 0; j < 4; ++j) kfa[j] = *(const LAS bf16x8*)KF_ADDR(0, j);
; #pragma unroll
;       for (int gi = 0; gi < 16; ++gi) {
;         if (gi + 1 < 16) {
; #pragma unroll
;           for (int j = 0; j < 4; ++j) { if (gi & 1) kfa[j] = *(const LAS bf16x8*)KF_ADDR(gi + 1, j); else kfb[j] = *(const LAS bf16x8*)KF_ADDR(gi + 1, j); } }
; #pragma unroll
;         for (int j = 0; j < 4; ++j) S[gi >> 1] = __builtin_amdgcn_mfma_f32_32x32x16_bf16((gi & 1) ? kfb[j] : kfa[j], qreg[(gi & 1) * 4 + j], S[gi >> 1], 0, 0, 0);
;         __builtin_amdgcn_sched_barrier(0);
;       }
	v_mfma_f32_32x32x16_bf16 v[96:111], v[12:15], v[132:135], v[96:111]
	ds_read_b128 v[4:7], v24 offset:32768
	ds_read_b128 v[8:11], v25 offset:32768
	ds_read_b128 v[12:15], v26 offset:32768
	ds_read_b128 v[16:19], v27 offset:32768
	s_waitcnt lgkmcnt(4)
	v_mfma_f32_32x32x16_bf16 v[96:111], v[20:23], v[128:131], v[96:111]
	s_waitcnt lgkmcnt(3)
	v_mfma_f32_32x32x16_bf16 v[80:95], v[4:7], v[0:3], 0
	s_waitcnt lgkmcnt(2)
	v_mfma_f32_32x32x16_bf16 v[80:95], v[8:11], v[152:155], v[80:95]
	s_waitcnt lgkmcnt(1)
	v_mfma_f32_32x32x16_bf16 v[80:95], v[12:15], v[148:151], v[80:95]
	ds_read_b128 v[4:7], v28 offset:32768
	ds_read_b128 v[8:11], v29 offset:32768
	ds_read_b128 v[12:15], v30 offset:32768
	ds_read_b128 v[20:23], v31 offset:32768
	s_waitcnt lgkmcnt(4)
	v_mfma_f32_32x32x16_bf16 v[80:95], v[16:19], v[144:147], v[80:95]
	s_waitcnt lgkmcnt(3)
	v_mfma_f32_32x32x16_bf16 v[80:95], v[4:7], v[140:143], v[80:95]
	s_waitcnt lgkmcnt(2)
	v_mfma_f32_32x32x16_bf16 v[80:95], v[8:11], v[136:139], v[80:95]
	s_waitcnt lgkmcnt(1)
	v_mfma_f32_32x32x16_bf16 v[80:95], v[12:15], v[132:135], v[80:95]
	ds_read_b128 v[4:7], v24 offset:49152
	ds_read_b128 v[8:11], v25 offset:49152
	ds_read_b128 v[12:15], v26 offset:49152
	ds_read_b128 v[16:19], v27 offset:49152
	s_waitcnt lgkmcnt(4)
	v_mfma_f32_32x32x16_bf16 v[80:95], v[20:23], v[128:131], v[80:95]
	s_waitcnt lgkmcnt(3)
	v_mfma_f32_32x32x16_bf16 v[64:79], v[4:7], v[0:3], 0
	s_waitcnt lgkmcnt(2)
	v_mfma_f32_32x32x16_bf16 v[64:79], v[8:11], v[152:155], v[64:79]
	s_waitcnt lgkmcnt(1)
	v_mfma_f32_32x32x16_bf16 v[64:79], v[12:15], v[148:151], v[64:79]
	ds_read_b128 v[4:7], v28 offset:49152
	ds_read_b128 v[8:11], v29 offset:49152
	ds_read_b128 v[12:15], v30 offset:49152
	ds_read_b128 v[20:23], v31 offset:49152
	s_waitcnt lgkmcnt(4)
	v_mfma_f32_32x32x16_bf16 v[64:79], v[16:19], v[144:147], v[64:79]
	s_waitcnt lgkmcnt(3)
	v_mfma_f32_32x32x16_bf16 v[64:79], v[4:7], v[140:143], v[64:79]
	v_add_u32_e32 v230, 0x10000, v173
	v_add_u32_e32 v4, v230, v209
	v_add_u32_e32 v16, v230, v218
	s_waitcnt lgkmcnt(2)
	v_mfma_f32_32x32x16_bf16 v[64:79], v[8:11], v[136:139], v[64:79]
	v_add_u32_e32 v8, v230, v210
	ds_read_b128 v[4:7], v4
	ds_read_b128 v[8:11], v8
	s_waitcnt lgkmcnt(3)
	v_mfma_f32_32x32x16_bf16 v[64:79], v[12:15], v[132:135], v[64:79]
	v_add_u32_e32 v12, v230, v211
	ds_read_b128 v[12:15], v12
	ds_read_b128 v[16:19], v16
	s_waitcnt lgkmcnt(4)
	v_mfma_f32_32x32x16_bf16 v[64:79], v[20:23], v[128:131], v[64:79]
	s_waitcnt lgkmcnt(3)
	v_mfma_f32_32x32x16_bf16 v[48:63], v[4:7], v[0:3], 0
	v_add_u32_e32 v4, v230, v226
	v_add_u32_e32 v20, v230, v229
	s_waitcnt lgkmcnt(2)
	v_mfma_f32_32x32x16_bf16 v[48:63], v[8:11], v[152:155], v[48:63]
	v_add_u32_e32 v8, v230, v227
	ds_read_b128 v[4:7], v4
	ds_read_b128 v[8:11], v8
	s_waitcnt lgkmcnt(3)
	v_mfma_f32_32x32x16_bf16 v[48:63], v[12:15], v[148:151], v[48:63]
	v_add_u32_e32 v12, v230, v228
	ds_read_b128 v[12:15], v12
	ds_read_b128 v[20:23], v20
	s_waitcnt lgkmcnt(4)
	v_mfma_f32_32x32x16_bf16 v[48:63], v[16:19], v[144:147], v[48:63]
	s_waitcnt lgkmcnt(3)
	v_mfma_f32_32x32x16_bf16 v[48:63], v[4:7], v[140:143], v[48:63]
	v_add_u32_e32 v231, 0x14000, v173
	v_add_u32_e32 v4, v231, v209
	v_add_u32_e32 v16, v231, v218
	s_waitcnt lgkmcnt(2)
	v_mfma_f32_32x32x16_bf16 v[48:63], v[8:11], v[136:139], v[48:63]
	v_add_u32_e32 v8, v231, v210
	ds_read_b128 v[4:7], v4
	ds_read_b128 v[8:11], v8
	s_waitcnt lgkmcnt(3)
	v_mfma_f32_32x32x16_bf16 v[48:63], v[12:15], v[132:135], v[48:63]
	v_add_u32_e32 v12, v231, v211
	ds_read_b128 v[12:15], v12
	ds_read_b128 v[16:19], v16
	s_waitcnt lgkmcnt(4)
	v_mfma_f32_32x32x16_bf16 v[48:63], v[20:23], v[128:131], v[48:63]
	s_waitcnt lgkmcnt(3)
	v_mfma_f32_32x32x16_bf16 v[32:47], v[4:7], v[0:3], 0
	v_add_u32_e32 v4, v231, v226
	v_add_u32_e32 v20, v231, v229
	s_waitcnt lgkmcnt(2)
	v_mfma_f32_32x32x16_bf16 v[32:47], v[8:11], v[152:155], v[32:47]
	v_add_u32_e32 v8, v231, v227
	ds_read_b128 v[4:7], v4
	ds_read_b128 v[8:11], v8
	s_waitcnt lgkmcnt(3)
	v_mfma_f32_32x32x16_bf16 v[32:47], v[12:15], v[148:151], v[32:47]
	v_add_u32_e32 v12, v231, v228
	ds_read_b128 v[12:15], v12
	ds_read_b128 v[20:23], v20
	s_waitcnt lgkmcnt(4)
	v_mfma_f32_32x32x16_bf16 v[32:47], v[16:19], v[144:147], v[32:47]
	s_waitcnt lgkmcnt(3)
	v_mfma_f32_32x32x16_bf16 v[32:47], v[4:7], v[140:143], v[32:47]
	v_add_u32_e32 v232, 0x18000, v173
	v_add_u32_e32 v4, v232, v209
	v_add_u32_e32 v16, v232, v218
	s_waitcnt lgkmcnt(2)
	v_mfma_f32_32x32x16_bf16 v[32:47], v[8:11], v[136:139], v[32:47]
	v_add_u32_e32 v8, v232, v210
	ds_read_b128 v[4:7], v4
	ds_read_b128 v[8:11], v8
	s_waitcnt lgkmcnt(3)
	v_mfma_f32_32x32x16_bf16 v[32:47], v[12:15], v[132:135], v[32:47]
	v_add_u32_e32 v12, v232, v211
	ds_read_b128 v[12:15], v12
	ds_read_b128 v[156:159], v16
	s_waitcnt lgkmcnt(4)
	v_mfma_f32_32x32x16_bf16 v[32:47], v[20:23], v[128:131], v[32:47]
	s_waitcnt lgkmcnt(3)
	v_mfma_f32_32x32x16_bf16 v[16:31], v[4:7], v[0:3], 0
	v_add_u32_e32 v4, v232, v226
	v_add_u32_e32 v214, v232, v229
	s_waitcnt lgkmcnt(2)
	v_mfma_f32_32x32x16_bf16 v[16:31], v[8:11], v[152:155], v[16:31]
	v_add_u32_e32 v8, v232, v227
	ds_read_b128 v[4:7], v4
	ds_read_b128 v[8:11], v8
	s_waitcnt lgkmcnt(3)
	v_mfma_f32_32x32x16_bf16 v[16:31], v[12:15], v[148:151], v[16:31]
	v_add_u32_e32 v12, v232, v228
	ds_read_b128 v[12:15], v12
	ds_read_b128 v[214:217], v214
	s_waitcnt lgkmcnt(4)
	v_mfma_f32_32x32x16_bf16 v[16:31], v[156:159], v[144:147], v[16:31]
	s_waitcnt lgkmcnt(3)
	v_mfma_f32_32x32x16_bf16 v[16:31], v[4:7], v[140:143], v[16:31]
	v_add_u32_e32 v233, 0x1c000, v173
	v_add_u32_e32 v4, v233, v209
	s_waitcnt lgkmcnt(2)
; #define LAS __attribute__((address_space(3)))
; DI void attn_prompt_item(const Params& p, int item, ldsp lds, int tid_) {
;     ...
;   for (int sh = 0; sh < 2; ++sh) {
;     if (sh == 1) {
;       __builtin_amdgcn_sched_barrier(0);
; #pragma unroll
;       for (int s = 0; s < 8; ++s) qreg[s] = *(const bf16x8*)(qx + qrow * D + h * 256 + 16 * (8 + s) + 8 * h2);
;     }
;     {
;       bf16x8 kfa[4], kfb[4];
;     ...
; #pragma unroll
;       for (int j = 0; j < 4; ++j) kfa[j] = *(const LAS bf16x8*)KF_ADDR(0, j);
; #pragma unroll
;       for (int gi = 0; gi < 16; ++gi) {
;         if (gi + 1 < 16) {
; #pragma unroll
;           for (int j = 0; j < 4; ++j) { if (gi & 1) kfa[j] = *(const LAS bf16x8*)KF_ADDR(gi + 1, j); else kfb[j] = *(const LAS bf16x8*)KF_ADDR(gi + 1, j); } }
; #pragma unroll
;         for (int j = 0; j < 4; ++j) S[gi >> 1] = __builtin_amdgcn_mfma_f32_32x32x16_bf16((gi & 1) ? kfb[j] : kfa[j], qreg[(gi & 1) * 4 + j], S[gi >> 1], 0, 0, 0);
;         __builtin_amdgcn_sched_barrier(0);
;       }
	v_mfma_f32_32x32x16_bf16 v[16:31], v[8:11], v[136:139], v[16:31]
	v_add_u32_e32 v8, v233, v210
	ds_read_b128 v[4:7], v4
	ds_read_b128 v[156:159], v8
	v_add_u32_e32 v8, v233, v211
	v_add_u32_e32 v9, v233, v218
	ds_read_b128 v[218:221], v8
	ds_read_b128 v[222:225], v9
	s_waitcnt lgkmcnt(5)
	v_mfma_f32_32x32x16_bf16 v[16:31], v[12:15], v[132:135], v[16:31]
	s_waitcnt lgkmcnt(4)
	v_mfma_f32_32x32x16_bf16 v[16:31], v[214:217], v[128:131], v[16:31]
	s_waitcnt lgkmcnt(3)
	v_mfma_f32_32x32x16_bf16 v[0:15], v[4:7], v[0:3], 0
	v_add_u32_e32 v209, v233, v229
	s_waitcnt lgkmcnt(2)
	v_mfma_f32_32x32x16_bf16 v[0:15], v[156:159], v[152:155], v[0:15]
	v_add_u32_e32 v152, v233, v226
	v_add_u32_e32 v153, v233, v227
	v_add_u32_e32 v156, v233, v228
	s_waitcnt lgkmcnt(1)
	v_mfma_f32_32x32x16_bf16 v[0:15], v[218:221], v[148:151], v[0:15]
	ds_read_b128 v[148:151], v152
	ds_read_b128 v[152:155], v153
	ds_read_b128 v[156:159], v156
	ds_read_b128 v[214:217], v209
	s_waitcnt lgkmcnt(4)
	v_mfma_f32_32x32x16_bf16 v[0:15], v[222:225], v[144:147], v[0:15]
	s_waitcnt lgkmcnt(3)
	v_mfma_f32_32x32x16_bf16 v[0:15], v[148:151], v[140:143], v[0:15]
	s_waitcnt lgkmcnt(2)
	v_mfma_f32_32x32x16_bf16 v[0:15], v[152:155], v[136:139], v[0:15]
	s_waitcnt lgkmcnt(1)
	v_mfma_f32_32x32x16_bf16 v[0:15], v[156:159], v[132:135], v[0:15]
	s_waitcnt lgkmcnt(0)
	v_mfma_f32_32x32x16_bf16 v[0:15], v[214:217], v[128:131], v[0:15]
	global_load_dwordx4 v[156:159], v[166:167], off offset:256
	global_load_dwordx4 v[152:155], v[166:167], off offset:288
	global_load_dwordx4 v[148:151], v[166:167], off offset:320
	global_load_dwordx4 v[144:147], v[166:167], off offset:352
	global_load_dwordx4 v[140:143], v[166:167], off offset:384
	global_load_dwordx4 v[136:139], v[166:167], off offset:416
	global_load_dwordx4 v[132:135], v[166:167], off offset:448
	global_load_dwordx4 v[128:131], v[166:167], off offset:480
	v_bitop3_b32 v166, v208, v175, 16 bitop3:0x36
	v_lshlrev_b32_e32 v166, 4, v166
	v_add_u32_e32 v167, v173, v166
	ds_read_b128 v[214:217], v167
	v_bitop3_b32 v209, v208, v175, 18 bitop3:0x36
	v_lshlrev_b32_e32 v234, 4, v209
	v_add_u32_e32 v235, v173, v234
	ds_read_b128 v[218:221], v235
	v_bitop3_b32 v209, v208, v175, 20 bitop3:0x36
	v_lshlrev_b32_e32 v236, 4, v209
	v_bitop3_b32 v209, v208, v175, 22 bitop3:0x36
	v_add_u32_e32 v237, v173, v236
	v_lshlrev_b32_e32 v238, 4, v209
	v_add_u32_e32 v239, v173, v238
	v_bitop3_b32 v209, v208, v175, 24 bitop3:0x36
	v_lshlrev_b32_e32 v240, 4, v209
	v_bitop3_b32 v209, v208, v175, 26 bitop3:0x36
	v_lshlrev_b32_e32 v242, 4, v209
	v_bitop3_b32 v209, v208, v175, 28 bitop3:0x36
	v_lshlrev_b32_e32 v244, 4, v209
	v_bitop3_b32 v208, v208, v175, 30 bitop3:0x36
	v_add_u32_e32 v241, v173, v240
	v_add_u32_e32 v245, v173, v244
	v_lshlrev_b32_e32 v246, 4, v208
	v_add_u32_e32 v243, v173, v242
	v_add_u32_e32 v247, v173, v246
	s_waitcnt vmcnt(7) lgkmcnt(1)
	v_mfma_f32_32x32x16_bf16 v[112:127], v[214:217], v[156:159], v[112:127]
	ds_read_b128 v[214:217], v237
	ds_read_b128 v[222:225], v239
	s_waitcnt vmcnt(6) lgkmcnt(2)
	v_mfma_f32_32x32x16_bf16 v[112:127], v[218:221], v[152:155], v[112:127]
	ds_read_b128 v[218:221], v241
	ds_read_b128 v[226:229], v243
	s_waitcnt vmcnt(5) lgkmcnt(3)
	v_mfma_f32_32x32x16_bf16 v[112:127], v[214:217], v[148:151], v[112:127]
	ds_read_b128 v[208:211], v245
	ds_read_b128 v[214:217], v247
	s_waitcnt vmcnt(4) lgkmcnt(4)
	v_mfma_f32_32x32x16_bf16 v[112:127], v[222:225], v[144:147], v[112:127]
	s_waitcnt vmcnt(3) lgkmcnt(3)
	v_mfma_f32_32x32x16_bf16 v[112:127], v[218:221], v[140:143], v[112:127]
	s_waitcnt vmcnt(2) lgkmcnt(2)
	v_mfma_f32_32x32x16_bf16 v[112:127], v[226:229], v[136:139], v[112:127]
	s_waitcnt vmcnt(1) lgkmcnt(1)
	v_mfma_f32_32x32x16_bf16 v[112:127], v[208:211], v[132:135], v[112:127]
	ds_read_b128 v[208:211], v167 offset:16384
	ds_read_b128 v[218:221], v235 offset:16384
	ds_read_b128 v[222:225], v237 offset:16384
	ds_read_b128 v[226:229], v239 offset:16384
	s_waitcnt vmcnt(0) lgkmcnt(4)
	v_mfma_f32_32x32x16_bf16 v[112:127], v[214:217], v[128:131], v[112:127]
	s_waitcnt lgkmcnt(3)
	v_mfma_f32_32x32x16_bf16 v[96:111], v[208:211], v[156:159], v[96:111]
	s_waitcnt lgkmcnt(2)
	v_mfma_f32_32x32x16_bf16 v[96:111], v[218:221], v[152:155], v[96:111]
	s_waitcnt lgkmcnt(1)
	v_mfma_f32_32x32x16_bf16 v[96:111], v[222:225], v[148:151], v[96:111]
	ds_read_b128 v[208:211], v241 offset:16384
	ds_read_b128 v[214:217], v243 offset:16384
	ds_read_b128 v[218:221], v245 offset:16384
	ds_read_b128 v[222:225], v247 offset:16384
	s_waitcnt lgkmcnt(4)
	v_mfma_f32_32x32x16_bf16 v[96:111], v[226:229], v[144:147], v[96:111]
	s_waitcnt lgkmcnt(3)
	v_mfma_f32_32x32x16_bf16 v[96:111], v[208:211], v[140:143], v[96:111]
	s_waitcnt lgkmcnt(2)
	v_mfma_f32_32x32x16_bf16 v[96:111], v[214:217], v[136:139], v[96:111]
	s_waitcnt lgkmcnt(1)
	v_mfma_f32_32x32x16_bf16 v[96:111], v[218:221], v[132:135], v[96:111]
	ds_read_b128 v[208:211], v167 offset:32768
	ds_read_b128 v[214:217], v235 offset:32768
	ds_read_b128 v[218:221], v237 offset:32768
	ds_read_b128 v[226:229], v239 offset:32768
	s_waitcnt lgkmcnt(4)
	v_mfma_f32_32x32x16_bf16 v[96:111], v[222:225], v[128:131], v[96:111]
	s_waitcnt lgkmcnt(3)
	v_mfma_f32_32x32x16_bf16 v[80:95], v[208:211], v[156:159], v[80:95]
	s_waitcnt lgkmcnt(2)
	v_mfma_f32_32x32x16_bf16 v[80:95], v[214:217], v[152:155], v[80:95]
	s_waitcnt lgkmcnt(1)
	v_mfma_f32_32x32x16_bf16 v[80:95], v[218:221], v[148:151], v[80:95]
	ds_read_b128 v[208:211], v241 offset:32768
	ds_read_b128 v[214:217], v243 offset:32768
	ds_read_b128 v[218:221], v245 offset:32768
	ds_read_b128 v[222:225], v247 offset:32768
	s_waitcnt lgkmcnt(4)
; #define LAS __attribute__((address_space(3)))
; DI void attn_prompt_item(const Params& p, int item, ldsp lds, int tid_) {
;     ...
;     {
;       bf16x8 kfa[4], kfb[4];
;     ...
; #pragma unroll
;       for (int j = 0; j < 4; ++j) kfa[j] = *(const LAS bf16x8*)KF_ADDR(0, j);
; #pragma unroll
;       for (int gi = 0; gi < 16; ++gi) {
;         if (gi + 1 < 16) {
; #pragma unroll
;           for (int j = 0; j < 4; ++j) { if (gi & 1) kfa[j] = *(const LAS bf16x8*)KF_ADDR(gi + 1, j); else kfb[j] = *(const LAS bf16x8*)KF_ADDR(gi + 1, j); } }
; #pragma unroll
;         for (int j = 0; j < 4; ++j) S[gi >> 1] = __builtin_amdgcn_mfma_f32_32x32x16_bf16((gi & 1) ? kfb[j] : kfa[j], qreg[(gi & 1) * 4 + j], S[gi >> 1], 0, 0, 0);
;         __builtin_amdgcn_sched_barrier(0);
;       }
	v_mfma_f32_32x32x16_bf16 v[80:95], v[226:229], v[144:147], v[80:95]
	s_waitcnt lgkmcnt(3)
	v_mfma_f32_32x32x16_bf16 v[80:95], v[208:211], v[140:143], v[80:95]
	s_waitcnt lgkmcnt(2)
	v_mfma_f32_32x32x16_bf16 v[80:95], v[214:217], v[136:139], v[80:95]
	s_waitcnt lgkmcnt(1)
	v_mfma_f32_32x32x16_bf16 v[80:95], v[218:221], v[132:135], v[80:95]
	ds_read_b128 v[208:211], v167 offset:49152
	ds_read_b128 v[214:217], v235 offset:49152
	ds_read_b128 v[218:221], v237 offset:49152
	ds_read_b128 v[226:229], v239 offset:49152
	s_waitcnt lgkmcnt(4)
	v_mfma_f32_32x32x16_bf16 v[80:95], v[222:225], v[128:131], v[80:95]
	s_waitcnt lgkmcnt(3)
	v_mfma_f32_32x32x16_bf16 v[64:79], v[208:211], v[156:159], v[64:79]
	s_waitcnt lgkmcnt(2)
	v_mfma_f32_32x32x16_bf16 v[64:79], v[214:217], v[152:155], v[64:79]
	s_waitcnt lgkmcnt(1)
	v_mfma_f32_32x32x16_bf16 v[64:79], v[218:221], v[148:151], v[64:79]
	ds_read_b128 v[208:211], v241 offset:49152
	ds_read_b128 v[214:217], v243 offset:49152
	ds_read_b128 v[218:221], v245 offset:49152
	ds_read_b128 v[222:225], v247 offset:49152
	s_waitcnt lgkmcnt(4)
	v_mfma_f32_32x32x16_bf16 v[64:79], v[226:229], v[144:147], v[64:79]
	s_waitcnt lgkmcnt(3)
	v_mfma_f32_32x32x16_bf16 v[64:79], v[208:211], v[140:143], v[64:79]
	v_add_u32_e32 v167, v230, v166
	v_add_u32_e32 v226, v230, v238
	s_waitcnt lgkmcnt(2)
	v_mfma_f32_32x32x16_bf16 v[64:79], v[214:217], v[136:139], v[64:79]
	v_add_u32_e32 v214, v230, v234
	ds_read_b128 v[208:211], v167
	ds_read_b128 v[214:217], v214
	v_add_u32_e32 v167, v230, v236
	s_waitcnt lgkmcnt(3)
	v_mfma_f32_32x32x16_bf16 v[64:79], v[218:221], v[132:135], v[64:79]
	ds_read_b128 v[218:221], v167
	ds_read_b128 v[226:229], v226
	s_waitcnt lgkmcnt(4)
	v_mfma_f32_32x32x16_bf16 v[64:79], v[222:225], v[128:131], v[64:79]
	s_waitcnt lgkmcnt(3)
	v_mfma_f32_32x32x16_bf16 v[48:63], v[208:211], v[156:159], v[48:63]
	v_add_u32_e32 v167, v230, v240
	v_add_u32_e32 v222, v230, v246
	s_waitcnt lgkmcnt(2)
	v_mfma_f32_32x32x16_bf16 v[48:63], v[214:217], v[152:155], v[48:63]
	v_add_u32_e32 v214, v230, v242
	ds_read_b128 v[208:211], v167
	ds_read_b128 v[214:217], v214
	v_add_u32_e32 v167, v230, v244
	s_waitcnt lgkmcnt(3)
	v_mfma_f32_32x32x16_bf16 v[48:63], v[218:221], v[148:151], v[48:63]
	ds_read_b128 v[218:221], v167
	ds_read_b128 v[222:225], v222
	s_waitcnt lgkmcnt(4)
	v_mfma_f32_32x32x16_bf16 v[48:63], v[226:229], v[144:147], v[48:63]
	s_waitcnt lgkmcnt(3)
	v_mfma_f32_32x32x16_bf16 v[48:63], v[208:211], v[140:143], v[48:63]
	v_add_u32_e32 v167, v231, v166
	v_add_u32_e32 v226, v231, v238
	s_waitcnt lgkmcnt(2)
	v_mfma_f32_32x32x16_bf16 v[48:63], v[214:217], v[136:139], v[48:63]
	v_add_u32_e32 v214, v231, v234
	ds_read_b128 v[208:211], v167
	ds_read_b128 v[214:217], v214
	v_add_u32_e32 v167, v231, v236
	s_waitcnt lgkmcnt(3)
	v_mfma_f32_32x32x16_bf16 v[48:63], v[218:221], v[132:135], v[48:63]
	ds_read_b128 v[218:221], v167
	ds_read_b128 v[226:229], v226
	s_waitcnt lgkmcnt(4)
	v_mfma_f32_32x32x16_bf16 v[48:63], v[222:225], v[128:131], v[48:63]
	s_waitcnt lgkmcnt(3)
	v_mfma_f32_32x32x16_bf16 v[32:47], v[208:211], v[156:159], v[32:47]
	v_add_u32_e32 v167, v231, v240
	v_add_u32_e32 v222, v231, v246
	s_waitcnt lgkmcnt(2)
	v_mfma_f32_32x32x16_bf16 v[32:47], v[214:217], v[152:155], v[32:47]
	v_add_u32_e32 v214, v231, v242
	ds_read_b128 v[208:211], v167
	ds_read_b128 v[214:217], v214
	v_add_u32_e32 v167, v231, v244
	s_waitcnt lgkmcnt(3)
	v_mfma_f32_32x32x16_bf16 v[32:47], v[218:221], v[148:151], v[32:47]
	ds_read_b128 v[218:221], v167
	ds_read_b128 v[222:225], v222
	s_waitcnt lgkmcnt(4)
	v_mfma_f32_32x32x16_bf16 v[32:47], v[226:229], v[144:147], v[32:47]
	s_waitcnt lgkmcnt(3)
	v_mfma_f32_32x32x16_bf16 v[32:47], v[208:211], v[140:143], v[32:47]
	v_add_u32_e32 v167, v232, v166
	v_add_u32_e32 v226, v232, v238
	s_waitcnt lgkmcnt(2)
	v_mfma_f32_32x32x16_bf16 v[32:47], v[214:217], v[136:139], v[32:47]
	v_add_u32_e32 v214, v232, v234
	ds_read_b128 v[208:211], v167
	ds_read_b128 v[214:217], v214
	v_add_u32_e32 v167, v232, v236
	s_waitcnt lgkmcnt(3)
	v_mfma_f32_32x32x16_bf16 v[32:47], v[218:221], v[132:135], v[32:47]
	ds_read_b128 v[218:221], v167
	ds_read_b128 v[226:229], v226
	s_waitcnt lgkmcnt(4)
	v_mfma_f32_32x32x16_bf16 v[32:47], v[222:225], v[128:131], v[32:47]
	s_waitcnt lgkmcnt(3)
	v_mfma_f32_32x32x16_bf16 v[16:31], v[208:211], v[156:159], v[16:31]
	v_add_u32_e32 v167, v232, v240
	v_add_u32_e32 v222, v232, v246
	s_waitcnt lgkmcnt(2)
	v_mfma_f32_32x32x16_bf16 v[16:31], v[214:217], v[152:155], v[16:31]
	v_add_u32_e32 v214, v232, v242
	ds_read_b128 v[208:211], v167
	ds_read_b128 v[214:217], v214
	v_add_u32_e32 v167, v232, v244
	s_waitcnt lgkmcnt(3)
	v_mfma_f32_32x32x16_bf16 v[16:31], v[218:221], v[148:151], v[16:31]
	ds_read_b128 v[218:221], v167
	ds_read_b128 v[222:225], v222
	s_waitcnt lgkmcnt(4)
	v_mfma_f32_32x32x16_bf16 v[16:31], v[226:229], v[144:147], v[16:31]
	s_waitcnt lgkmcnt(3)
	v_mfma_f32_32x32x16_bf16 v[16:31], v[208:211], v[140:143], v[16:31]
	v_add_u32_e32 v166, v233, v166
	v_add_u32_e32 v167, v233, v234
	s_waitcnt lgkmcnt(2)
	v_mfma_f32_32x32x16_bf16 v[16:31], v[214:217], v[136:139], v[16:31]
	ds_read_b128 v[208:211], v166
	ds_read_b128 v[214:217], v167
	v_add_u32_e32 v166, v233, v236
	v_add_u32_e32 v167, v233, v238
	s_waitcnt lgkmcnt(3)
	v_mfma_f32_32x32x16_bf16 v[16:31], v[218:221], v[132:135], v[16:31]
	ds_read_b128 v[218:221], v166
	ds_read_b128 v[226:229], v167
	s_waitcnt lgkmcnt(4)
	v_mfma_f32_32x32x16_bf16 v[16:31], v[222:225], v[128:131], v[16:31]
	s_waitcnt lgkmcnt(3)
	v_mfma_f32_32x32x16_bf16 v[0:15], v[208:211], v[156:159], v[0:15]
	v_add_u32_e32 v156, v233, v244
	v_add_u32_e32 v166, v233, v246
	s_waitcnt lgkmcnt(2)
; DI void attn_prompt_item(const Params& p, int item, ldsp lds, int tid_) {
;     ...
;         for (int j = 0; j < 4; ++j) S[gi >> 1] = __builtin_amdgcn_mfma_f32_32x32x16_bf16((gi & 1) ? kfb[j] : kfa[j], qreg[(gi & 1) * 4 + j], S[gi >> 1], 0, 0, 0);
;         __builtin_amdgcn_sched_barrier(0);
;       }
;     ...
;     }
;   }
;   float mx = -1e30f;
; #pragma unroll
;   for (int kt = 0; kt < 8; ++kt)
; #pragma unroll
;     for (int i = 0; i < 16; ++i) mx = fmaxf(mx, S[kt][i]);
;   mx = fmaxf(mx, __shfl_xor(mx, 32));
;   float sum = 0.f;
; #pragma unroll
;   for (int kt = 0; kt < 8; ++kt)
; #pragma unroll
;     for (int i = 0; i < 16; ++i) { const float e = __expf(S[kt][i] - mx); S[kt][i] = e; sum += e; }
;   sum += __shfl_xor(sum, 32);
;   const float inv = 1.f / sum;
	v_mfma_f32_32x32x16_bf16 v[0:15], v[214:217], v[152:155], v[0:15]
	v_add_u32_e32 v152, v233, v240
	v_add_u32_e32 v153, v233, v242
	s_waitcnt lgkmcnt(1)
	v_mfma_f32_32x32x16_bf16 v[0:15], v[218:221], v[148:151], v[0:15]
	ds_read_b128 v[148:151], v152
	ds_read_b128 v[152:155], v153
	ds_read_b128 v[156:159], v156
	ds_read_b128 v[208:211], v166
	s_waitcnt lgkmcnt(4)
	v_mfma_f32_32x32x16_bf16 v[0:15], v[226:229], v[144:147], v[0:15]
	s_waitcnt lgkmcnt(3)
	v_mfma_f32_32x32x16_bf16 v[0:15], v[148:151], v[140:143], v[0:15]
	s_waitcnt lgkmcnt(2)
	v_mfma_f32_32x32x16_bf16 v[0:15], v[152:155], v[136:139], v[0:15]
	s_waitcnt lgkmcnt(1)
	v_mfma_f32_32x32x16_bf16 v[0:15], v[156:159], v[132:135], v[0:15]
	s_waitcnt lgkmcnt(0)
	v_mfma_f32_32x32x16_bf16 v[0:15], v[208:211], v[128:131], v[0:15]
	v_max3_f32 v128, v112, s35, v113
	v_max3_f32 v128, v128, v114, v115
	v_max3_f32 v128, v128, v116, v117
	v_max3_f32 v128, v128, v118, v119
	v_max3_f32 v128, v128, v120, v121
	v_max3_f32 v128, v128, v122, v123
	v_max3_f32 v128, v128, v124, v125
	v_max3_f32 v128, v128, v126, v127
	v_max3_f32 v128, v128, v96, v97
	v_max3_f32 v128, v128, v98, v99
	v_max3_f32 v128, v128, v100, v101
	v_max3_f32 v128, v128, v102, v103
	v_max3_f32 v128, v128, v104, v105
	v_max3_f32 v128, v128, v106, v107
	v_max3_f32 v128, v128, v108, v109
	v_max3_f32 v128, v128, v110, v111
	v_max3_f32 v128, v128, v80, v81
	v_max3_f32 v128, v128, v82, v83
	v_max3_f32 v128, v128, v84, v85
	v_max3_f32 v128, v128, v86, v87
	v_max3_f32 v128, v128, v88, v89
	v_max3_f32 v128, v128, v90, v91
	v_max3_f32 v128, v128, v92, v93
	v_max3_f32 v128, v128, v94, v95
	v_max3_f32 v128, v128, v64, v65
	v_max3_f32 v128, v128, v66, v67
	v_max3_f32 v128, v128, v68, v69
	v_max3_f32 v128, v128, v70, v71
	v_max3_f32 v128, v128, v72, v73
	v_max3_f32 v128, v128, v74, v75
	v_max3_f32 v128, v128, v76, v77
	v_max3_f32 v128, v128, v78, v79
	v_max3_f32 v128, v128, v48, v49
	v_max3_f32 v128, v128, v50, v51
	v_max3_f32 v128, v128, v52, v53
	v_max3_f32 v128, v128, v54, v55
	v_max3_f32 v128, v128, v56, v57
	v_max3_f32 v128, v128, v58, v59
	v_max3_f32 v128, v128, v60, v61
	v_max3_f32 v128, v128, v62, v63
	v_max3_f32 v128, v128, v32, v33
	v_max3_f32 v128, v128, v34, v35
	v_max3_f32 v128, v128, v36, v37
	v_max3_f32 v128, v128, v38, v39
	v_max3_f32 v128, v128, v40, v41
	v_max3_f32 v128, v128, v42, v43
	v_max3_f32 v128, v128, v44, v45
	v_max3_f32 v128, v128, v46, v47
	v_max3_f32 v128, v128, v16, v17
	v_max3_f32 v128, v128, v18, v19
	v_max3_f32 v128, v128, v20, v21
	v_max3_f32 v128, v128, v22, v23
	v_max3_f32 v128, v128, v24, v25
	v_max3_f32 v128, v128, v26, v27
	v_max3_f32 v128, v128, v28, v29
	v_max3_f32 v128, v128, v30, v31
	v_max3_f32 v128, v128, v0, v1
	v_max3_f32 v128, v128, v2, v3
	v_max3_f32 v128, v128, v4, v5
	v_max3_f32 v128, v128, v6, v7
	v_max3_f32 v128, v128, v8, v9
	v_max3_f32 v128, v128, v10, v11
	v_cmp_lt_i32_e32 vcc, v169, v170
	v_max3_f32 v128, v128, v12, v13
	v_max3_f32 v128, v128, v14, v15
	v_cndmask_b32_e32 v129, v168, v169, vcc
	v_lshlrev_b32_e32 v132, 2, v129
	ds_bpermute_b32 v129, v132, v128
	s_lshl_b32 s28, s28, 10
	s_or_b32 s3, s3, s28
	s_waitcnt lgkmcnt(0)
	s_barrier
	v_max_f32_e32 v129, v129, v129
	v_max_f32_e32 v134, v128, v129
	v_sub_f32_e32 v112, v112, v134
	v_sub_f32_e32 v113, v113, v134
	v_mul_f32_e32 v112, 0x3fb8aa3b, v112
	v_exp_f32_e32 v133, v112
	v_mul_f32_e32 v112, 0x3fb8aa3b, v113
	v_exp_f32_e32 v135, v112
	v_sub_f32_e32 v112, v114, v134
	v_mul_f32_e32 v112, 0x3fb8aa3b, v112
	v_exp_f32_e32 v136, v112
	v_sub_f32_e32 v112, v115, v134
	v_mul_f32_e32 v112, 0x3fb8aa3b, v112
	v_exp_f32_e32 v137, v112
	v_add_f32_e32 v112, 0, v133
	v_add_f32_e32 v112, v135, v112
	v_add_f32_e32 v112, v136, v112
	v_add_f32_e32 v114, v137, v112
	v_sub_f32_e32 v112, v116, v134
	v_mul_f32_e32 v112, 0x3fb8aa3b, v112
	v_exp_f32_e32 v138, v112
	v_sub_f32_e32 v112, v117, v134
	v_mul_f32_e32 v112, 0x3fb8aa3b, v112
	v_exp_f32_e32 v139, v112
	v_sub_f32_e32 v112, v118, v134
	v_mul_f32_e32 v112, 0x3fb8aa3b, v112
	v_sub_f32_e32 v113, v119, v134
	v_exp_f32_e32 v112, v112
	v_mul_f32_e32 v113, 0x3fb8aa3b, v113
	v_exp_f32_e32 v113, v113
	v_add_f32_e32 v114, v138, v114
	v_add_f32_e32 v114, v139, v114
	v_add_f32_e32 v114, v112, v114
	v_add_f32_e32 v118, v113, v114
	v_sub_f32_e32 v114, v120, v134
	v_mul_f32_e32 v114, 0x3fb8aa3b, v114
	v_sub_f32_e32 v115, v121, v134
	v_exp_f32_e32 v114, v114
	v_mul_f32_e32 v115, 0x3fb8aa3b, v115
	v_sub_f32_e32 v116, v122, v134
	v_exp_f32_e32 v115, v115
	v_mul_f32_e32 v116, 0x3fb8aa3b, v116
	v_sub_f32_e32 v117, v123, v134
	v_exp_f32_e32 v116, v116
	v_mul_f32_e32 v117, 0x3fb8aa3b, v117
	v_exp_f32_e32 v117, v117
	v_add_f32_e32 v118, v114, v118
	v_add_f32_e32 v118, v115, v118
	v_add_f32_e32 v118, v116, v118
	v_add_f32_e32 v122, v117, v118
	v_sub_f32_e32 v118, v124, v134
	v_mul_f32_e32 v118, 0x3fb8aa3b, v118
	v_sub_f32_e32 v119, v125, v134
	v_exp_f32_e32 v118, v118
	v_mul_f32_e32 v119, 0x3fb8aa3b, v119
	v_sub_f32_e32 v120, v126, v134
	v_exp_f32_e32 v119, v119
	v_mul_f32_e32 v120, 0x3fb8aa3b, v120
	v_sub_f32_e32 v121, v127, v134
	v_exp_f32_e32 v120, v120
	v_mul_f32_e32 v121, 0x3fb8aa3b, v121
	v_sub_f32_e32 v96, v96, v134
	v_exp_f32_e32 v121, v121
	v_mul_f32_e32 v96, 0x3fb8aa3b, v96
	v_sub_f32_e32 v97, v97, v134
	v_add_f32_e32 v122, v118, v122
	v_exp_f32_e32 v96, v96
	v_mul_f32_e32 v97, 0x3fb8aa3b, v97
	v_sub_f32_e32 v98, v98, v134
	v_add_f32_e32 v122, v119, v122
	v_exp_f32_e32 v97, v97
	v_mul_f32_e32 v98, 0x3fb8aa3b, v98
	v_sub_f32_e32 v99, v99, v134
	v_add_f32_e32 v122, v120, v122
	v_exp_f32_e32 v98, v98
	v_mul_f32_e32 v99, 0x3fb8aa3b, v99
	v_sub_f32_e32 v100, v100, v134
	v_add_f32_e32 v122, v121, v122
	v_exp_f32_e32 v99, v99
; DI void attn_prompt_item(const Params& p, int item, ldsp lds, int tid_) {
;     ...
;   for (int kt = 0; kt < 8; ++kt)
; #pragma unroll
;     for (int i = 0; i < 16; ++i) { const float e = __expf(S[kt][i] - mx); S[kt][i] = e; sum += e; }
	v_mul_f32_e32 v100, 0x3fb8aa3b, v100
	v_sub_f32_e32 v101, v101, v134
	v_add_f32_e32 v122, v96, v122
	v_exp_f32_e32 v100, v100
	v_mul_f32_e32 v101, 0x3fb8aa3b, v101
	v_sub_f32_e32 v102, v102, v134
	v_add_f32_e32 v122, v97, v122
	v_exp_f32_e32 v101, v101
	v_mul_f32_e32 v102, 0x3fb8aa3b, v102
	v_sub_f32_e32 v103, v103, v134
	v_add_f32_e32 v122, v98, v122
	v_exp_f32_e32 v102, v102
	v_mul_f32_e32 v103, 0x3fb8aa3b, v103
	v_sub_f32_e32 v104, v104, v134
	v_add_f32_e32 v122, v99, v122
	v_exp_f32_e32 v103, v103
	v_mul_f32_e32 v104, 0x3fb8aa3b, v104
	v_sub_f32_e32 v105, v105, v134
	v_sub_f32_e32 v108, v108, v134
	v_add_f32_e32 v122, v100, v122
	v_exp_f32_e32 v104, v104
	v_mul_f32_e32 v105, 0x3fb8aa3b, v105
	v_sub_f32_e32 v106, v106, v134
	v_mul_f32_e32 v108, 0x3fb8aa3b, v108
	v_add_f32_e32 v122, v101, v122
	v_exp_f32_e32 v105, v105
	v_mul_f32_e32 v106, 0x3fb8aa3b, v106
	v_sub_f32_e32 v107, v107, v134
	v_exp_f32_e32 v128, v108
	v_sub_f32_e32 v108, v109, v134
	v_add_f32_e32 v122, v102, v122
	v_exp_f32_e32 v106, v106
	v_mul_f32_e32 v107, 0x3fb8aa3b, v107
	v_mul_f32_e32 v108, 0x3fb8aa3b, v108
	v_add_f32_e32 v122, v103, v122
	v_exp_f32_e32 v107, v107
	v_exp_f32_e32 v129, v108
	v_sub_f32_e32 v108, v110, v134
	v_add_f32_e32 v122, v104, v122
	v_mul_f32_e32 v108, 0x3fb8aa3b, v108
	v_add_f32_e32 v122, v105, v122
	v_exp_f32_e32 v130, v108
	v_sub_f32_e32 v108, v111, v134
	v_add_f32_e32 v122, v106, v122
	v_mul_f32_e32 v108, 0x3fb8aa3b, v108
	v_sub_f32_e32 v80, v80, v134
	v_add_f32_e32 v122, v107, v122
	v_exp_f32_e32 v131, v108
	v_mul_f32_e32 v80, 0x3fb8aa3b, v80
	v_sub_f32_e32 v81, v81, v134
	v_add_f32_e32 v108, v128, v122
	v_exp_f32_e32 v80, v80
	v_mul_f32_e32 v81, 0x3fb8aa3b, v81
	v_sub_f32_e32 v82, v82, v134
	v_add_f32_e32 v108, v129, v108
	v_exp_f32_e32 v81, v81
	v_mul_f32_e32 v82, 0x3fb8aa3b, v82
	v_sub_f32_e32 v83, v83, v134
	v_add_f32_e32 v108, v130, v108
	v_exp_f32_e32 v82, v82
	v_mul_f32_e32 v83, 0x3fb8aa3b, v83
	v_sub_f32_e32 v84, v84, v134
	v_add_f32_e32 v108, v131, v108
	v_exp_f32_e32 v83, v83
	v_mul_f32_e32 v84, 0x3fb8aa3b, v84
	v_sub_f32_e32 v85, v85, v134
	v_add_f32_e32 v108, v80, v108
	v_exp_f32_e32 v84, v84
	v_mul_f32_e32 v85, 0x3fb8aa3b, v85
	v_sub_f32_e32 v86, v86, v134
	v_add_f32_e32 v108, v81, v108
	v_exp_f32_e32 v85, v85
	v_mul_f32_e32 v86, 0x3fb8aa3b, v86
	v_sub_f32_e32 v87, v87, v134
	v_add_f32_e32 v108, v82, v108
	v_exp_f32_e32 v86, v86
	v_mul_f32_e32 v87, 0x3fb8aa3b, v87
	v_sub_f32_e32 v88, v88, v134
	v_add_f32_e32 v108, v83, v108
	v_exp_f32_e32 v87, v87
	v_mul_f32_e32 v88, 0x3fb8aa3b, v88
	v_sub_f32_e32 v89, v89, v134
	v_add_f32_e32 v108, v84, v108
	v_exp_f32_e32 v88, v88
	v_mul_f32_e32 v89, 0x3fb8aa3b, v89
	v_sub_f32_e32 v90, v90, v134
	v_add_f32_e32 v108, v85, v108
	v_exp_f32_e32 v89, v89
	v_mul_f32_e32 v90, 0x3fb8aa3b, v90
	v_sub_f32_e32 v91, v91, v134
	v_add_f32_e32 v108, v86, v108
	v_exp_f32_e32 v90, v90
	v_mul_f32_e32 v91, 0x3fb8aa3b, v91
	v_sub_f32_e32 v92, v92, v134
	v_add_f32_e32 v108, v87, v108
	v_exp_f32_e32 v91, v91
	v_mul_f32_e32 v92, 0x3fb8aa3b, v92
	v_sub_f32_e32 v93, v93, v134
	v_add_f32_e32 v108, v88, v108
	v_exp_f32_e32 v92, v92
	v_mul_f32_e32 v93, 0x3fb8aa3b, v93
	v_sub_f32_e32 v94, v94, v134
	v_add_f32_e32 v108, v89, v108
	v_exp_f32_e32 v93, v93
	v_mul_f32_e32 v94, 0x3fb8aa3b, v94
	v_sub_f32_e32 v95, v95, v134
	v_add_f32_e32 v108, v90, v108
	v_exp_f32_e32 v94, v94
	v_mul_f32_e32 v95, 0x3fb8aa3b, v95
	v_sub_f32_e32 v64, v64, v134
	v_add_f32_e32 v108, v91, v108
	v_exp_f32_e32 v95, v95
	v_mul_f32_e32 v64, 0x3fb8aa3b, v64
	v_sub_f32_e32 v65, v65, v134
	v_add_f32_e32 v108, v92, v108
	v_exp_f32_e32 v64, v64
	v_mul_f32_e32 v65, 0x3fb8aa3b, v65
	v_sub_f32_e32 v66, v66, v134
	v_add_f32_e32 v108, v93, v108
	v_exp_f32_e32 v65, v65
	v_mul_f32_e32 v66, 0x3fb8aa3b, v66
	v_sub_f32_e32 v67, v67, v134
	v_add_f32_e32 v108, v94, v108
	v_exp_f32_e32 v66, v66
	v_mul_f32_e32 v67, 0x3fb8aa3b, v67
	v_sub_f32_e32 v68, v68, v134
	v_add_f32_e32 v108, v95, v108
	v_exp_f32_e32 v67, v67
	v_mul_f32_e32 v68, 0x3fb8aa3b, v68
	v_sub_f32_e32 v69, v69, v134
	v_add_f32_e32 v108, v64, v108
	v_exp_f32_e32 v68, v68
	v_mul_f32_e32 v69, 0x3fb8aa3b, v69
	v_sub_f32_e32 v70, v70, v134
	v_add_f32_e32 v108, v65, v108
	v_exp_f32_e32 v69, v69
	v_mul_f32_e32 v70, 0x3fb8aa3b, v70
	v_sub_f32_e32 v71, v71, v134
	v_add_f32_e32 v108, v66, v108
	v_exp_f32_e32 v70, v70
	v_mul_f32_e32 v71, 0x3fb8aa3b, v71
	v_sub_f32_e32 v72, v72, v134
	v_add_f32_e32 v108, v67, v108
	v_exp_f32_e32 v71, v71
	v_mul_f32_e32 v72, 0x3fb8aa3b, v72
	v_sub_f32_e32 v73, v73, v134
	v_add_f32_e32 v108, v68, v108
	v_exp_f32_e32 v72, v72
	v_mul_f32_e32 v73, 0x3fb8aa3b, v73
	v_sub_f32_e32 v74, v74, v134
	v_add_f32_e32 v108, v69, v108
	v_exp_f32_e32 v73, v73
	v_mul_f32_e32 v74, 0x3fb8aa3b, v74
	v_sub_f32_e32 v75, v75, v134
	v_add_f32_e32 v108, v70, v108
	v_exp_f32_e32 v74, v74
	v_mul_f32_e32 v75, 0x3fb8aa3b, v75
	v_sub_f32_e32 v76, v76, v134
	v_add_f32_e32 v108, v71, v108
	v_exp_f32_e32 v75, v75
	v_mul_f32_e32 v76, 0x3fb8aa3b, v76
	v_sub_f32_e32 v77, v77, v134
	v_add_f32_e32 v108, v72, v108
	v_exp_f32_e32 v76, v76
	v_mul_f32_e32 v77, 0x3fb8aa3b, v77
	v_sub_f32_e32 v78, v78, v134
	v_add_f32_e32 v108, v73, v108
	v_exp_f32_e32 v77, v77
	v_mul_f32_e32 v78, 0x3fb8aa3b, v78
	v_sub_f32_e32 v79, v79, v134
	v_add_f32_e32 v108, v74, v108
	v_exp_f32_e32 v78, v78
	v_mul_f32_e32 v79, 0x3fb8aa3b, v79
	v_sub_f32_e32 v48, v48, v134
	v_add_f32_e32 v108, v75, v108
	v_exp_f32_e32 v79, v79
	v_mul_f32_e32 v48, 0x3fb8aa3b, v48
	v_sub_f32_e32 v49, v49, v134
	v_add_f32_e32 v108, v76, v108
	v_exp_f32_e32 v48, v48
	v_mul_f32_e32 v49, 0x3fb8aa3b, v49
	v_sub_f32_e32 v50, v50, v134
	v_add_f32_e32 v108, v77, v108
	v_exp_f32_e32 v49, v49
; DI void attn_prompt_item(const Params& p, int item, ldsp lds, int tid_) {
;     ...
;   for (int kt = 0; kt < 8; ++kt)
; #pragma unroll
;     for (int i = 0; i < 16; ++i) { const float e = __expf(S[kt][i] - mx); S[kt][i] = e; sum += e; }
	v_mul_f32_e32 v50, 0x3fb8aa3b, v50
	v_sub_f32_e32 v51, v51, v134
	v_add_f32_e32 v108, v78, v108
	v_exp_f32_e32 v50, v50
	v_mul_f32_e32 v51, 0x3fb8aa3b, v51
	v_sub_f32_e32 v52, v52, v134
	v_add_f32_e32 v108, v79, v108
	v_exp_f32_e32 v51, v51
	v_mul_f32_e32 v52, 0x3fb8aa3b, v52
	v_sub_f32_e32 v53, v53, v134
	v_add_f32_e32 v108, v48, v108
	v_exp_f32_e32 v52, v52
	v_mul_f32_e32 v53, 0x3fb8aa3b, v53
	v_sub_f32_e32 v54, v54, v134
	v_add_f32_e32 v108, v49, v108
	v_exp_f32_e32 v53, v53
	v_mul_f32_e32 v54, 0x3fb8aa3b, v54
	v_sub_f32_e32 v55, v55, v134
	v_add_f32_e32 v108, v50, v108
	v_exp_f32_e32 v54, v54
	v_mul_f32_e32 v55, 0x3fb8aa3b, v55
	v_sub_f32_e32 v56, v56, v134
	v_add_f32_e32 v108, v51, v108
	v_exp_f32_e32 v55, v55
	v_mul_f32_e32 v56, 0x3fb8aa3b, v56
	v_sub_f32_e32 v57, v57, v134
	v_add_f32_e32 v108, v52, v108
	v_exp_f32_e32 v56, v56
	v_mul_f32_e32 v57, 0x3fb8aa3b, v57
	v_sub_f32_e32 v58, v58, v134
	v_add_f32_e32 v108, v53, v108
	v_exp_f32_e32 v57, v57
	v_mul_f32_e32 v58, 0x3fb8aa3b, v58
	v_sub_f32_e32 v59, v59, v134
	v_add_f32_e32 v108, v54, v108
	v_exp_f32_e32 v58, v58
	v_mul_f32_e32 v59, 0x3fb8aa3b, v59
	v_sub_f32_e32 v60, v60, v134
	v_add_f32_e32 v108, v55, v108
	v_exp_f32_e32 v59, v59
	v_mul_f32_e32 v60, 0x3fb8aa3b, v60
	v_sub_f32_e32 v61, v61, v134
	v_add_f32_e32 v108, v56, v108
	v_exp_f32_e32 v60, v60
	v_mul_f32_e32 v61, 0x3fb8aa3b, v61
	v_sub_f32_e32 v62, v62, v134
	v_add_f32_e32 v108, v57, v108
	v_exp_f32_e32 v61, v61
	v_mul_f32_e32 v62, 0x3fb8aa3b, v62
	v_sub_f32_e32 v63, v63, v134
	v_sub_f32_e32 v36, v36, v134
	v_add_f32_e32 v108, v58, v108
	v_exp_f32_e32 v62, v62
	v_mul_f32_e32 v63, 0x3fb8aa3b, v63
	v_sub_f32_e32 v32, v32, v134
	v_mul_f32_e32 v36, 0x3fb8aa3b, v36
	v_add_f32_e32 v108, v59, v108
	v_exp_f32_e32 v63, v63
	v_mul_f32_e32 v32, 0x3fb8aa3b, v32
	v_sub_f32_e32 v33, v33, v134
	v_exp_f32_e32 v152, v36
	v_sub_f32_e32 v36, v37, v134
	v_sub_f32_e32 v37, v40, v134
	v_add_f32_e32 v108, v60, v108
	v_exp_f32_e32 v32, v32
	v_mul_f32_e32 v33, 0x3fb8aa3b, v33
	v_sub_f32_e32 v34, v34, v134
	v_mul_f32_e32 v37, 0x3fb8aa3b, v37
	v_add_f32_e32 v108, v61, v108
	v_exp_f32_e32 v33, v33
	v_mul_f32_e32 v34, 0x3fb8aa3b, v34
	v_sub_f32_e32 v35, v35, v134
	v_exp_f32_e32 v156, v37
	v_sub_f32_e32 v37, v41, v134
	v_add_f32_e32 v108, v62, v108
	v_exp_f32_e32 v34, v34
	v_mul_f32_e32 v35, 0x3fb8aa3b, v35
	v_mul_f32_e32 v36, 0x3fb8aa3b, v36
	v_mul_f32_e32 v37, 0x3fb8aa3b, v37
	v_add_f32_e32 v108, v63, v108
	v_exp_f32_e32 v35, v35
	v_exp_f32_e32 v153, v36
	v_sub_f32_e32 v36, v38, v134
	v_exp_f32_e32 v157, v37
	v_sub_f32_e32 v37, v42, v134
	v_add_f32_e32 v108, v32, v108
	v_mul_f32_e32 v36, 0x3fb8aa3b, v36
	v_mul_f32_e32 v37, 0x3fb8aa3b, v37
	v_add_f32_e32 v108, v33, v108
	v_exp_f32_e32 v154, v36
	v_sub_f32_e32 v36, v39, v134
	v_exp_f32_e32 v158, v37
	v_sub_f32_e32 v37, v43, v134
	v_sub_f32_e32 v16, v16, v134
	v_add_f32_e32 v108, v34, v108
	v_mul_f32_e32 v36, 0x3fb8aa3b, v36
	v_mul_f32_e32 v37, 0x3fb8aa3b, v37
	v_mul_f32_e32 v16, 0x3fb8aa3b, v16
	v_add_f32_e32 v108, v35, v108
	v_exp_f32_e32 v155, v36
	v_exp_f32_e32 v159, v37
	v_sub_f32_e32 v37, v44, v134
	v_exp_f32_e32 v210, v16
	v_sub_f32_e32 v16, v17, v134
	v_sub_f32_e32 v17, v20, v134
	v_add_f32_e32 v36, v152, v108
	v_mul_f32_e32 v37, 0x3fb8aa3b, v37
	v_mul_f32_e32 v17, 0x3fb8aa3b, v17
	v_add_f32_e32 v36, v153, v36
	v_exp_f32_e32 v166, v37
	v_sub_f32_e32 v37, v45, v134
	v_exp_f32_e32 v216, v17
	v_sub_f32_e32 v17, v21, v134
	v_add_f32_e32 v36, v154, v36
	v_mul_f32_e32 v37, 0x3fb8aa3b, v37
	v_mul_f32_e32 v17, 0x3fb8aa3b, v17
	v_add_f32_e32 v36, v155, v36
	v_exp_f32_e32 v167, v37
	v_sub_f32_e32 v37, v46, v134
	v_exp_f32_e32 v217, v17
	v_sub_f32_e32 v17, v22, v134
	v_add_f32_e32 v36, v156, v36
	v_mul_f32_e32 v37, 0x3fb8aa3b, v37
	v_mul_f32_e32 v17, 0x3fb8aa3b, v17
	v_add_f32_e32 v36, v157, v36
	v_exp_f32_e32 v208, v37
	v_sub_f32_e32 v37, v47, v134
	v_exp_f32_e32 v218, v17
	v_sub_f32_e32 v17, v23, v134
	v_add_f32_e32 v36, v158, v36
	v_mul_f32_e32 v37, 0x3fb8aa3b, v37
	v_mul_f32_e32 v16, 0x3fb8aa3b, v16
	v_mul_f32_e32 v17, 0x3fb8aa3b, v17
	v_add_f32_e32 v36, v159, v36
	v_exp_f32_e32 v209, v37
	v_exp_f32_e32 v211, v16
	v_sub_f32_e32 v16, v18, v134
	v_exp_f32_e32 v219, v17
	v_sub_f32_e32 v17, v24, v134
	v_add_f32_e32 v36, v166, v36
	v_mul_f32_e32 v16, 0x3fb8aa3b, v16
	v_mul_f32_e32 v17, 0x3fb8aa3b, v17
	v_add_f32_e32 v36, v167, v36
	v_exp_f32_e32 v214, v16
	v_sub_f32_e32 v16, v19, v134
	v_exp_f32_e32 v220, v17
	v_sub_f32_e32 v17, v25, v134
	v_add_f32_e32 v36, v208, v36
	v_mul_f32_e32 v16, 0x3fb8aa3b, v16
	v_mul_f32_e32 v17, 0x3fb8aa3b, v17
	v_add_f32_e32 v36, v209, v36
	v_exp_f32_e32 v215, v16
	v_exp_f32_e32 v221, v17
	v_sub_f32_e32 v17, v26, v134
	v_add_f32_e32 v16, v210, v36
	v_mul_f32_e32 v17, 0x3fb8aa3b, v17
	v_add_f32_e32 v16, v211, v16
	v_exp_f32_e32 v222, v17
	v_sub_f32_e32 v17, v27, v134
	v_sub_f32_e32 v0, v0, v134
	v_add_f32_e32 v16, v214, v16
	v_mul_f32_e32 v17, 0x3fb8aa3b, v17
	v_mul_f32_e32 v0, 0x3fb8aa3b, v0
	v_add_f32_e32 v16, v215, v16
	v_exp_f32_e32 v223, v17
	v_sub_f32_e32 v17, v28, v134
	v_exp_f32_e32 v228, v0
	v_sub_f32_e32 v0, v1, v134
	v_sub_f32_e32 v1, v4, v134
	v_add_f32_e32 v16, v216, v16
	v_mul_f32_e32 v17, 0x3fb8aa3b, v17
	v_mul_f32_e32 v1, 0x3fb8aa3b, v1
	v_add_f32_e32 v16, v217, v16
	v_exp_f32_e32 v224, v17
	v_sub_f32_e32 v17, v29, v134
	v_exp_f32_e32 v232, v1
	v_sub_f32_e32 v1, v5, v134
	v_add_f32_e32 v16, v218, v16
	v_mul_f32_e32 v17, 0x3fb8aa3b, v17
	v_mul_f32_e32 v1, 0x3fb8aa3b, v1
	v_add_f32_e32 v16, v219, v16
	v_exp_f32_e32 v225, v17
	v_sub_f32_e32 v17, v30, v134
	v_exp_f32_e32 v233, v1
	v_sub_f32_e32 v1, v6, v134
	v_add_f32_e32 v16, v220, v16
	v_mul_f32_e32 v17, 0x3fb8aa3b, v17
; #define LAS __attribute__((address_space(3)))
; DI unsigned pk2(float lo, float hi) { f32x2 v = {lo, hi}; return __builtin_bit_cast(unsigned, __builtin_convertvector(v, bf16x2v)); }
; DI void attn_prompt_item(const Params& p, int item, ldsp lds, int tid_) {
;     ...
;   sum += __shfl_xor(sum, 32);
;   const float inv = 1.f / sum;
;   bf16x8 pb[8][2];
; #pragma unroll
;   for (int kt = 0; kt < 8; ++kt)
; #pragma unroll
;     for (int s = 0; s < 2; ++s) {
;       u32x4 pw; pw.x = pk2(S[kt][8 * s], S[kt][8 * s + 1]); pw.y = pk2(S[kt][8 * s + 2], S[kt][8 * s + 3]); pw.z = pk2(S[kt][8 * s + 4], S[kt][8 * s + 5]); pw.w = pk2(S[kt][8 * s + 6], S[kt][8 * s + 7]);
;       pb[kt][s] = __builtin_bit_cast(bf16x8, pw);
;     }
;   __syncthreads();
; #pragma unroll
;   for (int hb = 0; hb < 2; ++hb) {
;     u32x4 vp[8];
; #pragma unroll
;     for (int i = 0; i < 8; ++i) { const int idx = tid + 512 * (hb * 8 + i), d = idx >> 5, c = idx & 31; vp[i] = ld16(mvt + ((size_t)((b * 4 + h) * 256 + d)) * 256 + c * 8); }
; #pragma unroll
;     for (int i = 0; i < 8; ++i) { const int idx = tid + 512 * (hb * 8 + i), d = idx >> 5, c = idx & 31; *(LAS u32x4*)(lds + d * 512 + ((c ^ (d & 15)) * 16)) = vp[i]; }
;   }
;   __syncthreads();
	v_mul_f32_e32 v1, 0x3fb8aa3b, v1
	v_add_f32_e32 v16, v221, v16
	v_exp_f32_e32 v226, v17
	v_sub_f32_e32 v17, v31, v134
	v_exp_f32_e32 v234, v1
	v_sub_f32_e32 v1, v7, v134
	v_add_f32_e32 v16, v222, v16
	v_mul_f32_e32 v17, 0x3fb8aa3b, v17
	v_mul_f32_e32 v0, 0x3fb8aa3b, v0
	v_mul_f32_e32 v1, 0x3fb8aa3b, v1
	v_add_f32_e32 v16, v223, v16
	v_exp_f32_e32 v227, v17
	v_exp_f32_e32 v229, v0
	v_sub_f32_e32 v0, v2, v134
	v_exp_f32_e32 v235, v1
	v_sub_f32_e32 v1, v8, v134
	v_add_f32_e32 v16, v224, v16
	v_mul_f32_e32 v0, 0x3fb8aa3b, v0
	v_mul_f32_e32 v1, 0x3fb8aa3b, v1
	v_add_f32_e32 v16, v225, v16
	v_exp_f32_e32 v230, v0
	v_sub_f32_e32 v0, v3, v134
	v_exp_f32_e32 v236, v1
	v_sub_f32_e32 v1, v9, v134
	v_add_f32_e32 v16, v226, v16
	v_mul_f32_e32 v0, 0x3fb8aa3b, v0
	v_mul_f32_e32 v1, 0x3fb8aa3b, v1
	v_add_f32_e32 v16, v227, v16
	v_exp_f32_e32 v231, v0
	v_exp_f32_e32 v237, v1
	v_sub_f32_e32 v1, v10, v134
	v_add_f32_e32 v0, v228, v16
	v_mul_f32_e32 v1, 0x3fb8aa3b, v1
	v_add_f32_e32 v0, v229, v0
	v_exp_f32_e32 v238, v1
	v_sub_f32_e32 v1, v11, v134
	v_add_f32_e32 v0, v230, v0
	v_mul_f32_e32 v1, 0x3fb8aa3b, v1
	v_add_f32_e32 v0, v231, v0
	v_exp_f32_e32 v239, v1
	v_sub_f32_e32 v1, v12, v134
	v_add_f32_e32 v0, v232, v0
	v_mul_f32_e32 v1, 0x3fb8aa3b, v1
	v_add_f32_e32 v0, v233, v0
	v_exp_f32_e32 v240, v1
	v_sub_f32_e32 v1, v13, v134
	v_add_f32_e32 v0, v234, v0
	v_mul_f32_e32 v1, 0x3fb8aa3b, v1
	v_add_f32_e32 v0, v235, v0
	v_exp_f32_e32 v241, v1
	v_sub_f32_e32 v1, v14, v134
	v_add_f32_e32 v0, v236, v0
	v_mul_f32_e32 v1, 0x3fb8aa3b, v1
	v_add_f32_e32 v0, v237, v0
	v_exp_f32_e32 v242, v1
	v_sub_f32_e32 v1, v15, v134
	v_add_f32_e32 v0, v238, v0
	v_mul_f32_e32 v1, 0x3fb8aa3b, v1
	v_add_f32_e32 v0, v239, v0
	v_exp_f32_e32 v243, v1
	v_add_f32_e32 v0, v240, v0
	v_add_f32_e32 v0, v241, v0
	v_add_f32_e32 v0, v242, v0
	v_add_f32_e32 v0, v243, v0
	ds_bpermute_b32 v1, v132, v0
	v_add_u32_e32 v2, s3, v177
	v_add_u32_e32 v8, s3, v178
	v_add_u32_e32 v10, s3, v180
	v_add_u32_e32 v16, s3, v181
	s_waitcnt lgkmcnt(0)
	v_add_f32_e32 v244, v0, v1
	v_add_u32_e32 v0, s3, v176
	v_add_u32_e32 v18, s3, v183
	v_add_u32_e32 v24, s3, v184
	v_add_u32_e32 v26, s3, v186
	v_add_u32_e32 v36, s3, v195
	v_add_u32_e32 v38, s3, v197
	v_add_u32_e32 v44, s3, v199
	v_add_u32_e32 v46, s3, v201
	v_ashrrev_i32_e32 v1, 31, v0
	v_ashrrev_i32_e32 v3, 31, v2
	v_ashrrev_i32_e32 v9, 31, v8
	v_ashrrev_i32_e32 v11, 31, v10
	v_ashrrev_i32_e32 v17, 31, v16
	v_ashrrev_i32_e32 v19, 31, v18
	v_ashrrev_i32_e32 v25, 31, v24
	v_ashrrev_i32_e32 v27, 31, v26
	v_ashrrev_i32_e32 v37, 31, v36
	v_ashrrev_i32_e32 v39, 31, v38
	v_ashrrev_i32_e32 v45, 31, v44
	v_ashrrev_i32_e32 v47, 31, v46
	v_lshl_add_u64 v[122:123], s[6:7], 0, v[164:165]
	v_lshlrev_b64 v[0:1], 9, v[0:1]
	v_lshlrev_b64 v[2:3], 9, v[2:3]
	v_lshlrev_b64 v[8:9], 9, v[8:9]
	v_lshlrev_b64 v[10:11], 9, v[10:11]
	v_lshlrev_b64 v[16:17], 9, v[16:17]
	v_lshlrev_b64 v[18:19], 9, v[18:19]
	v_lshlrev_b64 v[24:25], 9, v[24:25]
	v_lshlrev_b64 v[26:27], 9, v[26:27]
	v_lshlrev_b64 v[36:37], 9, v[36:37]
	v_lshlrev_b64 v[38:39], 9, v[38:39]
	v_lshlrev_b64 v[44:45], 9, v[44:45]
	v_lshlrev_b64 v[46:47], 9, v[46:47]
	v_lshl_add_u64 v[0:1], v[122:123], 0, v[0:1]
	v_lshl_add_u64 v[4:5], v[122:123], 0, v[2:3]
	v_lshl_add_u64 v[8:9], v[122:123], 0, v[8:9]
	v_lshl_add_u64 v[12:13], v[122:123], 0, v[10:11]
	v_lshl_add_u64 v[16:17], v[122:123], 0, v[16:17]
	v_lshl_add_u64 v[20:21], v[122:123], 0, v[18:19]
	v_lshl_add_u64 v[24:25], v[122:123], 0, v[24:25]
	v_lshl_add_u64 v[28:29], v[122:123], 0, v[26:27]
	v_lshl_add_u64 v[36:37], v[122:123], 0, v[36:37]
	v_lshl_add_u64 v[40:41], v[122:123], 0, v[38:39]
	v_lshl_add_u64 v[44:45], v[122:123], 0, v[44:45]
	v_lshl_add_u64 v[124:125], v[122:123], 0, v[46:47]
	v_cvt_pk_bf16_f32 v108, v133, v135
	global_load_dwordx4 v[0:3], v[0:1], off
	s_nop 0
	global_load_dwordx4 v[4:7], v[4:5], off
	s_nop 0
	global_load_dwordx4 v[8:11], v[8:9], off
	s_nop 0
	global_load_dwordx4 v[12:15], v[12:13], off
	s_nop 0
	global_load_dwordx4 v[16:19], v[16:17], off
	s_nop 0
	global_load_dwordx4 v[20:23], v[20:21], off
	s_nop 0
	global_load_dwordx4 v[24:27], v[24:25], off
	s_nop 0
	global_load_dwordx4 v[28:31], v[28:29], off
	s_nop 0
	global_load_dwordx4 v[36:39], v[36:37], off
	s_nop 0
	global_load_dwordx4 v[40:43], v[40:41], off
	s_nop 0
	global_load_dwordx4 v[44:47], v[44:45], off
	s_nop 0
	global_load_dwordx4 v[132:135], v[124:125], off
	v_add_u32_e32 v124, s3, v203
	v_ashrrev_i32_e32 v125, 31, v124
	v_add_u32_e32 v126, s3, v204
	v_lshlrev_b64 v[124:125], 9, v[124:125]
	v_ashrrev_i32_e32 v127, 31, v126
	v_lshl_add_u64 v[124:125], v[122:123], 0, v[124:125]
	v_lshlrev_b64 v[126:127], 9, v[126:127]
	v_cvt_pk_bf16_f32 v109, v136, v137
	v_cvt_pk_bf16_f32 v110, v138, v139
	v_lshl_add_u64 v[126:127], v[122:123], 0, v[126:127]
	global_load_dwordx4 v[136:139], v[124:125], off
	global_load_dwordx4 v[140:143], v[126:127], off
	v_add_u32_e32 v124, s3, v206
	v_ashrrev_i32_e32 v125, 31, v124
	v_add_u32_e32 v126, s3, v207
	v_lshlrev_b64 v[124:125], 9, v[124:125]
	v_ashrrev_i32_e32 v127, 31, v126
	v_lshl_add_u64 v[124:125], v[122:123], 0, v[124:125]
	v_lshlrev_b64 v[126:127], 9, v[126:127]
	v_lshl_add_u64 v[122:123], v[122:123], 0, v[126:127]
	global_load_dwordx4 v[144:147], v[124:125], off
	global_load_dwordx4 v[148:151], v[122:123], off
	s_waitcnt vmcnt(15)
	ds_write_b128 v179, v[0:3]
	s_waitcnt vmcnt(14)
	ds_write_b128 v182, v[4:7]
	s_waitcnt vmcnt(13)
	ds_write_b128 v185, v[8:11]
	s_waitcnt vmcnt(12)
	ds_write_b128 v187, v[12:15]
	s_waitcnt vmcnt(11)
	ds_write_b128 v188, v[16:19]
	s_waitcnt vmcnt(10)
	ds_write_b128 v189, v[20:23]
	s_waitcnt vmcnt(9)
	ds_write_b128 v190, v[24:27]
	s_waitcnt vmcnt(8)
	ds_write_b128 v191, v[28:31]
	s_waitcnt vmcnt(7)
	ds_write_b128 v192, v[36:39]
	s_waitcnt vmcnt(6)
	ds_write_b128 v193, v[40:43]
	s_waitcnt vmcnt(5)
	ds_write_b128 v194, v[44:47]
	s_waitcnt vmcnt(4)
	ds_write_b128 v196, v[132:135]
	s_waitcnt vmcnt(3)
	ds_write_b128 v200, v[136:139]
	v_div_scale_f32 v12, s[28:29], v244, v244, 1.0
	v_rcp_f32_e32 v13, v12
	s_waitcnt vmcnt(2)
	ds_write_b128 v198, v[140:143]
	s_waitcnt vmcnt(1)
	ds_write_b128 v202, v[144:147]
	s_waitcnt vmcnt(0)
	ds_write_b128 v205, v[148:151]
	v_and_b32_e32 v146, 0xf0, v174
	v_bitop3_b32 v139, v174, 16, v171 bitop3:0x6c
	v_fma_f32 v0, -v12, v13, 1.0
	v_add3_u32 v14, v173, v146, v160
	v_add3_u32 v15, v173, v139, v160
	v_fmac_f32_e32 v13, v0, v13
	s_waitcnt lgkmcnt(0)
	s_barrier
; #define LAS __attribute__((address_space(3)))
; DI unsigned pk2(float lo, float hi) { f32x2 v = {lo, hi}; return __builtin_bit_cast(unsigned, __builtin_convertvector(v, bf16x2v)); }
; DI void attn_prompt_item(const Params& p, int item, ldsp lds, int tid_) {
;     ...
;   bf16x8 pb[8][2];
; #pragma unroll
;   for (int kt = 0; kt < 8; ++kt)
; #pragma unroll
;     for (int s = 0; s < 2; ++s) {
;       u32x4 pw; pw.x = pk2(S[kt][8 * s], S[kt][8 * s + 1]); pw.y = pk2(S[kt][8 * s + 2], S[kt][8 * s + 3]); pw.z = pk2(S[kt][8 * s + 4], S[kt][8 * s + 5]); pw.w = pk2(S[kt][8 * s + 6], S[kt][8 * s + 7]);
;       pb[kt][s] = __builtin_bit_cast(bf16x8, pw);
;     }
;   __syncthreads();
; #pragma unroll
;   for (int hb = 0; hb < 2; ++hb) {
;     u32x4 vp[8];
; #pragma unroll
;     for (int i = 0; i < 8; ++i) { const int idx = tid + 512 * (hb * 8 + i), d = idx >> 5, c = idx & 31; vp[i] = ld16(mvt + ((size_t)((b * 4 + h) * 256 + d)) * 256 + c * 8); }
; #pragma unroll
;     for (int i = 0; i < 8; ++i) { const int idx = tid + 512 * (hb * 8 + i), d = idx >> 5, c = idx & 31; *(LAS u32x4*)(lds + d * 512 + ((c ^ (d & 15)) * 16)) = vp[i]; }
;   }
;   __syncthreads();
; #pragma unroll
;   for (int dh = 0; dh < 2; ++dh) {
;     f32x16 O[4];
; #pragma unroll
;     for (int dt = 0; dt < 4; ++dt)
; #pragma unroll
;       for (int i = 0; i < 16; ++i) O[dt][i] = 0.f;
;     {
;       u32x2 va[4][2], vb[4][2];
;     ...
; #pragma unroll
;       for (int dt = 0; dt < 4; ++dt) { va[dt][0] = *(const LAS u32x2*)VF_ADDR(0, dt, 0); va[dt][1] = *(const LAS u32x2*)VF_ADDR(0, dt, 1); }
; #pragma unroll
;       for (int gi = 0; gi < 16; ++gi) {
;         if (gi + 1 < 16) {
; #pragma unroll
;           for (int dt = 0; dt < 4; ++dt) {
;             if (gi & 1) { va[dt][0] = *(const LAS u32x2*)VF_ADDR(gi + 1, dt, 0); va[dt][1] = *(const LAS u32x2*)VF_ADDR(gi + 1, dt, 1); }
;             else { vb[dt][0] = *(const LAS u32x2*)VF_ADDR(gi + 1, dt, 0); vb[dt][1] = *(const LAS u32x2*)VF_ADDR(gi + 1, dt, 1); } } }
; #pragma unroll
;         for (int dt = 0; dt < 4; ++dt) { const u32x2 lo = (gi & 1) ? vb[dt][0] : va[dt][0], hi = (gi & 1) ? vb[dt][1] : va[dt][1];
;           u32x4 vw; vw.x = lo.x; vw.y = lo.y; vw.z = hi.x; vw.w = hi.y;
;           O[dt] = __builtin_amdgcn_mfma_f32_32x32x16_bf16(__builtin_bit_cast(bf16x8, vw), pb[gi >> 1][gi & 1], O[dt], 0, 0, 0); }
;         __builtin_amdgcn_sched_barrier(0);
;       }
	ds_read2st64_b64 v[0:3], v14 offset1:32
	ds_read2st64_b64 v[4:7], v15 offset1:32
	v_div_scale_f32 v16, vcc, 1.0, v244, 1.0
	v_cvt_pk_bf16_f32 v111, v112, v113
	s_waitcnt lgkmcnt(1)
	v_mov_b32_e32 v8, v0
	v_mov_b32_e32 v9, v1
	s_waitcnt lgkmcnt(0)
	v_mov_b32_e32 v10, v4
	v_mov_b32_e32 v11, v5
	v_mul_f32_e32 v0, v16, v13
	v_fma_f32 v1, -v12, v0, v16
	v_fmac_f32_e32 v0, v1, v13
	v_fma_f32 v1, -v12, v0, v16
	v_cvt_pk_bf16_f32 v125, v116, v117
	v_cvt_pk_bf16_f32 v116, v104, v105
	v_cvt_pk_bf16_f32 v117, v106, v107
	v_cvt_pk_bf16_f32 v104, v88, v89
	v_cvt_pk_bf16_f32 v105, v90, v91
	v_cvt_pk_bf16_f32 v106, v92, v93
	v_cvt_pk_bf16_f32 v107, v94, v95
	v_cvt_pk_bf16_f32 v92, v48, v49
	v_cvt_pk_bf16_f32 v93, v50, v51
	v_cvt_pk_bf16_f32 v94, v52, v53
	v_cvt_pk_bf16_f32 v95, v54, v55
	v_cvt_pk_bf16_f32 v88, v56, v57
	v_cvt_pk_bf16_f32 v89, v58, v59
	v_cvt_pk_bf16_f32 v90, v60, v61
	v_cvt_pk_bf16_f32 v91, v62, v63
	v_mfma_f32_32x32x16_bf16 v[48:63], v[8:11], v[108:111], 0
	ds_read2st64_b64 v[8:11], v14 offset0:64 offset1:96
	v_mov_b32_e32 v4, v2
	v_mov_b32_e32 v5, v3
	v_div_fmas_f32 v12, v1, v13, v0
	ds_read2st64_b64 v[0:3], v15 offset0:64 offset1:96
	v_cvt_pk_bf16_f32 v126, v118, v119
	v_cvt_pk_bf16_f32 v118, v128, v129
	v_lshlrev_b32_e32 v129, 4, v175
	v_xor_b32_e32 v147, 32, v129
	v_xor_b32_e32 v148, 48, v129
	v_cvt_pk_bf16_f32 v112, v80, v81
	v_cvt_pk_bf16_f32 v81, v158, v159
	v_add3_u32 v149, v173, v147, v160
	v_add3_u32 v158, v173, v148, v160
	v_cvt_pk_bf16_f32 v124, v114, v115
	v_cvt_pk_bf16_f32 v119, v130, v131
	v_cvt_pk_bf16_f32 v115, v86, v87
	v_cvt_pk_bf16_f32 v86, v152, v153
	ds_read2st64_b64 v[130:133], v149 offset1:32
	ds_read2st64_b64 v[134:137], v158 offset1:32
	ds_read2st64_b64 v[140:143], v149 offset0:64 offset1:96
	ds_read2st64_b64 v[150:153], v158 offset0:64 offset1:96
	v_cvt_pk_bf16_f32 v114, v84, v85
	v_cvt_pk_bf16_f32 v84, v32, v33
	v_cvt_pk_bf16_f32 v85, v34, v35
	v_mfma_f32_32x32x16_bf16 v[32:47], v[4:7], v[108:111], 0
	s_waitcnt lgkmcnt(5)
	v_mov_b32_e32 v4, v8
	v_mov_b32_e32 v5, v9
	s_waitcnt lgkmcnt(4)
	v_mov_b32_e32 v6, v0
	v_mov_b32_e32 v7, v1
	v_mov_b32_e32 v0, v10
	v_mov_b32_e32 v1, v11
	v_cvt_pk_bf16_f32 v127, v120, v121
	v_cvt_pk_bf16_f32 v120, v96, v97
	v_cvt_pk_bf16_f32 v121, v98, v99
	v_cvt_pk_bf16_f32 v122, v100, v101
	v_cvt_pk_bf16_f32 v123, v102, v103
	v_cvt_pk_bf16_f32 v113, v82, v83
	v_cvt_pk_bf16_f32 v100, v64, v65
	v_cvt_pk_bf16_f32 v101, v66, v67
	v_cvt_pk_bf16_f32 v102, v68, v69
	v_cvt_pk_bf16_f32 v103, v70, v71
	v_cvt_pk_bf16_f32 v96, v72, v73
	v_cvt_pk_bf16_f32 v97, v74, v75
	v_cvt_pk_bf16_f32 v98, v76, v77
	v_cvt_pk_bf16_f32 v99, v78, v79
	v_cvt_pk_bf16_f32 v87, v154, v155
	v_cvt_pk_bf16_f32 v80, v156, v157
	v_cvt_pk_bf16_f32 v82, v166, v167
	v_cvt_pk_bf16_f32 v83, v208, v209
	v_cvt_pk_bf16_f32 v76, v210, v211
	v_cvt_pk_bf16_f32 v77, v214, v215
	v_cvt_pk_bf16_f32 v78, v216, v217
	v_cvt_pk_bf16_f32 v79, v218, v219
	v_cvt_pk_bf16_f32 v72, v220, v221
	v_cvt_pk_bf16_f32 v73, v222, v223
	v_cvt_pk_bf16_f32 v74, v224, v225
	v_cvt_pk_bf16_f32 v75, v226, v227
	v_cvt_pk_bf16_f32 v68, v228, v229
	v_cvt_pk_bf16_f32 v69, v230, v231
	v_cvt_pk_bf16_f32 v70, v232, v233
	v_cvt_pk_bf16_f32 v71, v234, v235
	v_cvt_pk_bf16_f32 v64, v236, v237
	v_cvt_pk_bf16_f32 v65, v238, v239
	v_cvt_pk_bf16_f32 v66, v240, v241
	v_cvt_pk_bf16_f32 v67, v242, v243
	v_div_fixup_f32 v128, v12, v244, 1.0
	v_mfma_f32_32x32x16_bf16 v[16:31], v[4:7], v[108:111], 0
	v_mfma_f32_32x32x16_bf16 v[0:15], v[0:3], v[108:111], 0
	s_waitcnt lgkmcnt(3)
	v_mov_b32_e32 v154, v130
	v_mov_b32_e32 v155, v131
	s_waitcnt lgkmcnt(2)
	v_mov_b32_e32 v156, v134
	v_mov_b32_e32 v157, v135
	v_mov_b32_e32 v134, v132
	v_mov_b32_e32 v135, v133
	s_waitcnt lgkmcnt(1)
	v_mov_b32_e32 v130, v140
	v_mov_b32_e32 v131, v141
	s_waitcnt lgkmcnt(0)
	v_mov_b32_e32 v132, v150
	v_mov_b32_e32 v133, v151
	v_xor_b32_e32 v144, 64, v129
	v_xor_b32_e32 v145, 0x50, v129
	v_add3_u32 v159, v173, v144, v160
	v_add3_u32 v182, v173, v145, v160
	v_mfma_f32_32x32x16_bf16 v[48:63], v[154:157], v[124:127], v[48:63]
	v_mov_b32_e32 v150, v142
	v_mov_b32_e32 v151, v143
	v_mfma_f32_32x32x16_bf16 v[32:47], v[134:137], v[124:127], v[32:47]
	v_mfma_f32_32x32x16_bf16 v[16:31], v[130:133], v[124:127], v[16:31]
	ds_read2st64_b64 v[130:133], v159 offset1:32
	ds_read2st64_b64 v[134:137], v182 offset1:32
	ds_read2st64_b64 v[154:157], v159 offset0:64 offset1:96
	ds_read2st64_b64 v[164:167], v182 offset0:64 offset1:96
	v_mfma_f32_32x32x16_bf16 v[0:15], v[150:153], v[124:127], v[0:15]
	s_waitcnt lgkmcnt(3)
	v_mov_b32_e32 v140, v130
	v_mov_b32_e32 v141, v131
	s_waitcnt lgkmcnt(2)
	v_mov_b32_e32 v142, v134
	v_mov_b32_e32 v143, v135
	v_mov_b32_e32 v134, v132
	v_mov_b32_e32 v135, v133
	s_waitcnt lgkmcnt(1)
	v_mov_b32_e32 v130, v154
	v_mov_b32_e32 v131, v155
	s_waitcnt lgkmcnt(0)
	v_mov_b32_e32 v132, v164
	v_mov_b32_e32 v133, v165
	v_mfma_f32_32x32x16_bf16 v[48:63], v[140:143], v[120:123], v[48:63]
	v_xor_b32_e32 v142, 0x60, v129
	v_xor_b32_e32 v143, 0x70, v129
	v_add3_u32 v183, v173, v142, v160
	v_add3_u32 v184, v173, v143, v160
	v_mov_b32_e32 v164, v156
	v_mov_b32_e32 v165, v157
	v_mfma_f32_32x32x16_bf16 v[32:47], v[134:137], v[120:123], v[32:47]
	v_mfma_f32_32x32x16_bf16 v[16:31], v[130:133], v[120:123], v[16:31]
	ds_read2st64_b64 v[130:133], v183 offset1:32
	ds_read2st64_b64 v[134:137], v184 offset1:32
	ds_read2st64_b64 v[150:153], v183 offset0:64 offset1:96
	ds_read2st64_b64 v[154:157], v184 offset0:64 offset1:96
	v_mfma_f32_32x32x16_bf16 v[0:15], v[164:167], v[120:123], v[0:15]
	s_waitcnt lgkmcnt(3)
	v_mov_b32_e32 v164, v130
	v_mov_b32_e32 v165, v131
	s_waitcnt lgkmcnt(2)
; #define LAS __attribute__((address_space(3)))
; DI void attn_prompt_item(const Params& p, int item, ldsp lds, int tid_) {
;     ...
;     {
;       u32x2 va[4][2], vb[4][2];
;     ...
; #pragma unroll
;       for (int dt = 0; dt < 4; ++dt) { va[dt][0] = *(const LAS u32x2*)VF_ADDR(0, dt, 0); va[dt][1] = *(const LAS u32x2*)VF_ADDR(0, dt, 1); }
; #pragma unroll
;       for (int gi = 0; gi < 16; ++gi) {
;         if (gi + 1 < 16) {
; #pragma unroll
;           for (int dt = 0; dt < 4; ++dt) {
;             if (gi & 1) { va[dt][0] = *(const LAS u32x2*)VF_ADDR(gi + 1, dt, 0); va[dt][1] = *(const LAS u32x2*)VF_ADDR(gi + 1, dt, 1); }
;             else { vb[dt][0] = *(const LAS u32x2*)VF_ADDR(gi + 1, dt, 0); vb[dt][1] = *(const LAS u32x2*)VF_ADDR(gi + 1, dt, 1); } } }
; #pragma unroll
;         for (int dt = 0; dt < 4; ++dt) { const u32x2 lo = (gi & 1) ? vb[dt][0] : va[dt][0], hi = (gi & 1) ? vb[dt][1] : va[dt][1];
;           u32x4 vw; vw.x = lo.x; vw.y = lo.y; vw.z = hi.x; vw.w = hi.y;
;           O[dt] = __builtin_amdgcn_mfma_f32_32x32x16_bf16(__builtin_bit_cast(bf16x8, vw), pb[gi >> 1][gi & 1], O[dt], 0, 0, 0); }
;         __builtin_amdgcn_sched_barrier(0);
;       }
	v_mov_b32_e32 v166, v134
	v_mov_b32_e32 v167, v135
	v_mov_b32_e32 v134, v132
	v_mov_b32_e32 v135, v133
	s_waitcnt lgkmcnt(1)
	v_mov_b32_e32 v130, v150
	v_mov_b32_e32 v131, v151
	s_waitcnt lgkmcnt(0)
	v_mov_b32_e32 v132, v154
	v_mov_b32_e32 v133, v155
	v_xor_b32_e32 v140, 0x80, v129
	v_xor_b32_e32 v141, 0x90, v129
	v_add3_u32 v185, v173, v140, v160
	v_add3_u32 v186, v173, v141, v160
	v_mfma_f32_32x32x16_bf16 v[48:63], v[164:167], v[116:119], v[48:63]
	v_mov_b32_e32 v154, v152
	v_mov_b32_e32 v155, v153
	v_mfma_f32_32x32x16_bf16 v[32:47], v[134:137], v[116:119], v[32:47]
	v_mfma_f32_32x32x16_bf16 v[16:31], v[130:133], v[116:119], v[16:31]
	ds_read2st64_b64 v[130:133], v185 offset1:32
	ds_read2st64_b64 v[134:137], v186 offset1:32
	ds_read2st64_b64 v[150:153], v185 offset0:64 offset1:96
	ds_read2st64_b64 v[164:167], v186 offset0:64 offset1:96
	v_mfma_f32_32x32x16_bf16 v[0:15], v[154:157], v[116:119], v[0:15]
	s_waitcnt lgkmcnt(2)
	v_mov_b32_e32 v156, v134
	v_mov_b32_e32 v157, v135
	v_mov_b32_e32 v134, v132
	v_mov_b32_e32 v135, v133
	v_mov_b32_e32 v154, v130
	v_mov_b32_e32 v155, v131
	s_waitcnt lgkmcnt(1)
	v_mov_b32_e32 v130, v150
	v_mov_b32_e32 v131, v151
	s_waitcnt lgkmcnt(0)
	v_mov_b32_e32 v132, v164
	v_mov_b32_e32 v133, v165
	v_mfma_f32_32x32x16_bf16 v[32:47], v[134:137], v[112:115], v[32:47]
	v_xor_b32_e32 v137, 0xa0, v129
	v_xor_b32_e32 v138, 0xb0, v129
	v_add3_u32 v187, v173, v137, v160
	v_add3_u32 v188, v173, v138, v160
	v_mov_b32_e32 v164, v152
	v_mov_b32_e32 v165, v153
	v_mfma_f32_32x32x16_bf16 v[48:63], v[154:157], v[112:115], v[48:63]
	v_mfma_f32_32x32x16_bf16 v[16:31], v[130:133], v[112:115], v[16:31]
	ds_read2st64_b64 v[130:133], v187 offset1:32
	ds_read2st64_b64 v[150:153], v188 offset1:32
	ds_read2st64_b64 v[154:157], v187 offset0:64 offset1:96
	ds_read2st64_b64 v[174:177], v188 offset0:64 offset1:96
	v_mfma_f32_32x32x16_bf16 v[0:15], v[164:167], v[112:115], v[0:15]
	s_waitcnt lgkmcnt(3)
	v_mov_b32_e32 v164, v130
	v_mov_b32_e32 v165, v131
	s_waitcnt lgkmcnt(2)
	v_mov_b32_e32 v166, v150
	v_mov_b32_e32 v167, v151
	v_mov_b32_e32 v150, v132
	v_mov_b32_e32 v151, v133
	s_waitcnt lgkmcnt(1)
	v_mov_b32_e32 v130, v154
	v_mov_b32_e32 v131, v155
	s_waitcnt lgkmcnt(0)
	v_mov_b32_e32 v132, v174
	v_mov_b32_e32 v133, v175
	v_xor_b32_e32 v135, 0xc0, v129
	v_xor_b32_e32 v136, 0xd0, v129
	v_add3_u32 v189, v173, v135, v160
	v_add3_u32 v190, v173, v136, v160
	v_mfma_f32_32x32x16_bf16 v[48:63], v[164:167], v[104:107], v[48:63]
	v_mov_b32_e32 v174, v156
	v_mov_b32_e32 v175, v157
	v_mfma_f32_32x32x16_bf16 v[32:47], v[150:153], v[104:107], v[32:47]
	v_mfma_f32_32x32x16_bf16 v[16:31], v[130:133], v[104:107], v[16:31]
	ds_read2st64_b64 v[130:133], v189 offset1:32
	ds_read2st64_b64 v[150:153], v190 offset1:32
	ds_read2st64_b64 v[154:157], v189 offset0:64 offset1:96
	ds_read2st64_b64 v[164:167], v190 offset0:64 offset1:96
	v_mfma_f32_32x32x16_bf16 v[0:15], v[174:177], v[104:107], v[0:15]
	s_waitcnt lgkmcnt(2)
	v_mov_b32_e32 v176, v150
	v_mov_b32_e32 v177, v151
	v_mov_b32_e32 v150, v132
	v_mov_b32_e32 v151, v133
	v_mov_b32_e32 v174, v130
	v_mov_b32_e32 v175, v131
	v_mfma_f32_32x32x16_bf16 v[32:47], v[150:153], v[100:103], v[32:47]
	s_waitcnt lgkmcnt(1)
	v_mov_b32_e32 v150, v154
	v_mov_b32_e32 v151, v155
	s_waitcnt lgkmcnt(0)
	v_mov_b32_e32 v152, v164
	v_mov_b32_e32 v153, v165
	v_xor_b32_e32 v133, 0xe0, v129
	v_xor_b32_e32 v134, 0xf0, v129
	v_add3_u32 v130, v173, v133, v160
	v_add3_u32 v131, v173, v134, v160
	v_mfma_f32_32x32x16_bf16 v[48:63], v[174:177], v[100:103], v[48:63]
	v_mov_b32_e32 v164, v156
	v_mov_b32_e32 v165, v157
	v_mfma_f32_32x32x16_bf16 v[16:31], v[150:153], v[100:103], v[16:31]
	ds_read2st64_b64 v[150:153], v130 offset1:32
	ds_read2st64_b64 v[154:157], v131 offset1:32
	ds_read2st64_b64 v[174:177], v130 offset0:64 offset1:96
	ds_read2st64_b64 v[178:181], v131 offset0:64 offset1:96
	v_mfma_f32_32x32x16_bf16 v[0:15], v[164:167], v[100:103], v[0:15]
	s_waitcnt lgkmcnt(3)
	v_mov_b32_e32 v164, v150
	v_mov_b32_e32 v165, v151
	s_waitcnt lgkmcnt(2)
	v_mov_b32_e32 v166, v154
	v_mov_b32_e32 v167, v155
	v_mov_b32_e32 v154, v152
	v_mov_b32_e32 v155, v153
	s_waitcnt lgkmcnt(1)
	v_mov_b32_e32 v150, v174
	v_mov_b32_e32 v151, v175
	s_waitcnt lgkmcnt(0)
	v_mov_b32_e32 v152, v178
	v_mov_b32_e32 v153, v179
	v_add3_u32 v132, v173, v129, v160
	v_mfma_f32_32x32x16_bf16 v[48:63], v[164:167], v[96:99], v[48:63]
	v_add_u32_e32 v164, 0x100, v132
	v_xor_b32_e32 v132, 16, v129
	v_mov_b32_e32 v178, v176
	v_mov_b32_e32 v179, v177
	v_mfma_f32_32x32x16_bf16 v[16:31], v[150:153], v[96:99], v[16:31]
	v_add3_u32 v150, v173, v132, v160
	v_add_u32_e32 v173, 0x100, v150
	v_mfma_f32_32x32x16_bf16 v[32:47], v[154:157], v[96:99], v[32:47]
	ds_read2st64_b64 v[154:157], v164 offset1:32
	ds_read2st64_b64 v[150:153], v173 offset1:32
	ds_read2st64_b64 v[164:167], v164 offset0:64 offset1:96
	ds_read2st64_b64 v[174:177], v173 offset0:64 offset1:96
	v_mfma_f32_32x32x16_bf16 v[0:15], v[178:181], v[96:99], v[0:15]
	s_waitcnt lgkmcnt(2)
	v_mov_b32_e32 v180, v150
	v_mov_b32_e32 v181, v151
	v_mov_b32_e32 v150, v156
	v_mov_b32_e32 v151, v157
	v_mov_b32_e32 v178, v154
	v_mov_b32_e32 v179, v155
	v_mfma_f32_32x32x16_bf16 v[32:47], v[150:153], v[92:95], v[32:47]
	s_waitcnt lgkmcnt(1)
	v_mov_b32_e32 v150, v164
	v_mov_b32_e32 v151, v165
	s_waitcnt lgkmcnt(0)
	v_mov_b32_e32 v152, v174
	v_mov_b32_e32 v153, v175
	v_add_u32_e32 v149, 0x100, v149
	v_add_u32_e32 v158, 0x100, v158
	v_mov_b32_e32 v174, v166
	v_mfma_f32_32x32x16_bf16 v[48:63], v[178:181], v[92:95], v[48:63]
	v_mov_b32_e32 v175, v167
	v_mfma_f32_32x32x16_bf16 v[16:31], v[150:153], v[92:95], v[16:31]
	ds_read2st64_b64 v[150:153], v149 offset1:32
	ds_read2st64_b64 v[154:157], v158 offset1:32
	ds_read2st64_b64 v[164:167], v149 offset0:64 offset1:96
	ds_read2st64_b64 v[178:181], v158 offset0:64 offset1:96
	v_mfma_f32_32x32x16_bf16 v[0:15], v[174:177], v[92:95], v[0:15]
	s_waitcnt lgkmcnt(3)
; #define LAS __attribute__((address_space(3)))
; DI void attn_prompt_item(const Params& p, int item, ldsp lds, int tid_) {
;     ...
;     {
;       u32x2 va[4][2], vb[4][2];
;     ...
; #pragma unroll
;       for (int dt = 0; dt < 4; ++dt) { va[dt][0] = *(const LAS u32x2*)VF_ADDR(0, dt, 0); va[dt][1] = *(const LAS u32x2*)VF_ADDR(0, dt, 1); }
; #pragma unroll
;       for (int gi = 0; gi < 16; ++gi) {
;         if (gi + 1 < 16) {
; #pragma unroll
;           for (int dt = 0; dt < 4; ++dt) {
;             if (gi & 1) { va[dt][0] = *(const LAS u32x2*)VF_ADDR(gi + 1, dt, 0); va[dt][1] = *(const LAS u32x2*)VF_ADDR(gi + 1, dt, 1); }
;             else { vb[dt][0] = *(const LAS u32x2*)VF_ADDR(gi + 1, dt, 0); vb[dt][1] = *(const LAS u32x2*)VF_ADDR(gi + 1, dt, 1); } } }
; #pragma unroll
;         for (int dt = 0; dt < 4; ++dt) { const u32x2 lo = (gi & 1) ? vb[dt][0] : va[dt][0], hi = (gi & 1) ? vb[dt][1] : va[dt][1];
;           u32x4 vw; vw.x = lo.x; vw.y = lo.y; vw.z = hi.x; vw.w = hi.y;
;           O[dt] = __builtin_amdgcn_mfma_f32_32x32x16_bf16(__builtin_bit_cast(bf16x8, vw), pb[gi >> 1][gi & 1], O[dt], 0, 0, 0); }
;         __builtin_amdgcn_sched_barrier(0);
;       }
	v_mov_b32_e32 v174, v150
	v_mov_b32_e32 v175, v151
	s_waitcnt lgkmcnt(2)
	v_mov_b32_e32 v176, v154
	v_mov_b32_e32 v177, v155
	v_mov_b32_e32 v154, v152
	v_mov_b32_e32 v155, v153
	s_waitcnt lgkmcnt(1)
	v_mov_b32_e32 v150, v164
	v_mov_b32_e32 v151, v165
	s_waitcnt lgkmcnt(0)
	v_mov_b32_e32 v152, v178
	v_mov_b32_e32 v153, v179
	v_add_u32_e32 v149, 0x100, v159
	v_add_u32_e32 v158, 0x100, v182
	v_mfma_f32_32x32x16_bf16 v[48:63], v[174:177], v[88:91], v[48:63]
	v_mov_b32_e32 v178, v166
	v_mov_b32_e32 v179, v167
	v_mfma_f32_32x32x16_bf16 v[32:47], v[154:157], v[88:91], v[32:47]
	v_mfma_f32_32x32x16_bf16 v[16:31], v[150:153], v[88:91], v[16:31]
	ds_read2st64_b64 v[150:153], v149 offset1:32
	ds_read2st64_b64 v[154:157], v158 offset1:32
	ds_read2st64_b64 v[164:167], v149 offset0:64 offset1:96
	ds_read2st64_b64 v[174:177], v158 offset0:64 offset1:96
	v_mfma_f32_32x32x16_bf16 v[0:15], v[178:181], v[88:91], v[0:15]
	s_waitcnt lgkmcnt(3)
	v_mov_b32_e32 v178, v150
	v_mov_b32_e32 v179, v151
	s_waitcnt lgkmcnt(2)
	v_mov_b32_e32 v180, v154
	v_mov_b32_e32 v181, v155
	v_mov_b32_e32 v154, v152
	v_mov_b32_e32 v155, v153
	s_waitcnt lgkmcnt(1)
	v_mov_b32_e32 v150, v164
	v_mov_b32_e32 v151, v165
	s_waitcnt lgkmcnt(0)
	v_mov_b32_e32 v152, v174
	v_mov_b32_e32 v153, v175
	v_add_u32_e32 v149, 0x100, v183
	v_add_u32_e32 v158, 0x100, v184
	v_mfma_f32_32x32x16_bf16 v[48:63], v[178:181], v[84:87], v[48:63]
	v_mov_b32_e32 v174, v166
	v_mov_b32_e32 v175, v167
	v_mfma_f32_32x32x16_bf16 v[32:47], v[154:157], v[84:87], v[32:47]
	v_mfma_f32_32x32x16_bf16 v[16:31], v[150:153], v[84:87], v[16:31]
	ds_read2st64_b64 v[150:153], v149 offset1:32
	ds_read2st64_b64 v[154:157], v158 offset1:32
	ds_read2st64_b64 v[164:167], v149 offset0:64 offset1:96
	ds_read2st64_b64 v[178:181], v158 offset0:64 offset1:96
	v_mfma_f32_32x32x16_bf16 v[0:15], v[174:177], v[84:87], v[0:15]
	s_waitcnt lgkmcnt(3)
	v_mov_b32_e32 v174, v150
	v_mov_b32_e32 v175, v151
	s_waitcnt lgkmcnt(2)
	v_mov_b32_e32 v176, v154
	v_mov_b32_e32 v177, v155
	v_mov_b32_e32 v154, v152
	v_mov_b32_e32 v155, v153
	s_waitcnt lgkmcnt(1)
	v_mov_b32_e32 v150, v164
	v_mov_b32_e32 v151, v165
	s_waitcnt lgkmcnt(0)
	v_mov_b32_e32 v152, v178
	v_mov_b32_e32 v153, v179
	v_add_u32_e32 v149, 0x100, v185
	v_add_u32_e32 v158, 0x100, v186
	v_mfma_f32_32x32x16_bf16 v[48:63], v[174:177], v[80:83], v[48:63]
	v_mov_b32_e32 v178, v166
	v_mov_b32_e32 v179, v167
	v_mfma_f32_32x32x16_bf16 v[32:47], v[154:157], v[80:83], v[32:47]
	v_mfma_f32_32x32x16_bf16 v[16:31], v[150:153], v[80:83], v[16:31]
	ds_read2st64_b64 v[150:153], v149 offset1:32
	ds_read2st64_b64 v[154:157], v158 offset1:32
	ds_read2st64_b64 v[164:167], v149 offset0:64 offset1:96
	ds_read2st64_b64 v[174:177], v158 offset0:64 offset1:96
	v_mfma_f32_32x32x16_bf16 v[0:15], v[178:181], v[80:83], v[0:15]
	s_waitcnt lgkmcnt(3)
	v_mov_b32_e32 v178, v150
	v_mov_b32_e32 v179, v151
	s_waitcnt lgkmcnt(2)
	v_mov_b32_e32 v180, v154
	v_mov_b32_e32 v181, v155
	v_mov_b32_e32 v154, v152
	v_mov_b32_e32 v155, v153
	s_waitcnt lgkmcnt(1)
	v_mov_b32_e32 v150, v164
	v_mov_b32_e32 v151, v165
	s_waitcnt lgkmcnt(0)
	v_mov_b32_e32 v152, v174
	v_mov_b32_e32 v153, v175
	v_add_u32_e32 v149, 0x100, v187
	v_add_u32_e32 v158, 0x100, v188
	v_mfma_f32_32x32x16_bf16 v[48:63], v[178:181], v[76:79], v[48:63]
	v_mov_b32_e32 v174, v166
	v_mov_b32_e32 v175, v167
	v_mfma_f32_32x32x16_bf16 v[32:47], v[154:157], v[76:79], v[32:47]
	v_mfma_f32_32x32x16_bf16 v[16:31], v[150:153], v[76:79], v[16:31]
	ds_read2st64_b64 v[150:153], v149 offset1:32
	ds_read2st64_b64 v[154:157], v158 offset1:32
	ds_read2st64_b64 v[164:167], v149 offset0:64 offset1:96
	ds_read2st64_b64 v[178:181], v158 offset0:64 offset1:96
	v_mfma_f32_32x32x16_bf16 v[0:15], v[174:177], v[76:79], v[0:15]
	s_waitcnt lgkmcnt(3)
	v_mov_b32_e32 v174, v150
	v_mov_b32_e32 v175, v151
	s_waitcnt lgkmcnt(2)
	v_mov_b32_e32 v176, v154
	v_mov_b32_e32 v177, v155
	v_mov_b32_e32 v154, v152
	v_mov_b32_e32 v155, v153
	s_waitcnt lgkmcnt(1)
	v_mov_b32_e32 v150, v164
	v_mov_b32_e32 v151, v165
	s_waitcnt lgkmcnt(0)
	v_mov_b32_e32 v152, v178
	v_mov_b32_e32 v153, v179
	v_add_u32_e32 v149, 0x100, v189
	v_add_u32_e32 v158, 0x100, v190
	v_mfma_f32_32x32x16_bf16 v[48:63], v[174:177], v[72:75], v[48:63]
	v_mov_b32_e32 v178, v166
	v_mov_b32_e32 v179, v167
	v_mfma_f32_32x32x16_bf16 v[32:47], v[154:157], v[72:75], v[32:47]
	v_mfma_f32_32x32x16_bf16 v[16:31], v[150:153], v[72:75], v[16:31]
	ds_read2st64_b64 v[150:153], v149 offset1:32
	ds_read2st64_b64 v[154:157], v158 offset1:32
	ds_read2st64_b64 v[164:167], v149 offset0:64 offset1:96
	ds_read2st64_b64 v[174:177], v158 offset0:64 offset1:96
	v_mfma_f32_32x32x16_bf16 v[0:15], v[178:181], v[72:75], v[0:15]
	s_waitcnt lgkmcnt(3)
	v_mov_b32_e32 v178, v150
	v_mov_b32_e32 v179, v151
	s_waitcnt lgkmcnt(2)
	v_mov_b32_e32 v180, v154
	v_mov_b32_e32 v181, v155
	v_mov_b32_e32 v154, v152
	v_mov_b32_e32 v155, v153
	s_waitcnt lgkmcnt(1)
	v_mov_b32_e32 v150, v164
	v_mov_b32_e32 v151, v165
	s_waitcnt lgkmcnt(0)
	v_mov_b32_e32 v152, v174
	v_mov_b32_e32 v153, v175
	v_add_u32_e32 v130, 0x100, v130
	v_add_u32_e32 v131, 0x100, v131
	v_mfma_f32_32x32x16_bf16 v[48:63], v[178:181], v[68:71], v[48:63]
	v_mov_b32_e32 v174, v166
	v_mov_b32_e32 v175, v167
	v_mfma_f32_32x32x16_bf16 v[32:47], v[154:157], v[68:71], v[32:47]
	v_mfma_f32_32x32x16_bf16 v[16:31], v[150:153], v[68:71], v[16:31]
	ds_read2st64_b64 v[150:153], v130 offset1:32
	ds_read2st64_b64 v[154:157], v131 offset1:32
	ds_read2st64_b64 v[164:167], v130 offset0:64 offset1:96
	ds_read2st64_b64 v[178:181], v131 offset0:64 offset1:96
	v_mfma_f32_32x32x16_bf16 v[0:15], v[174:177], v[68:71], v[0:15]
	s_waitcnt lgkmcnt(3)
; #define LAS __attribute__((address_space(3)))
; DI unsigned pk2(float lo, float hi) { f32x2 v = {lo, hi}; return __builtin_bit_cast(unsigned, __builtin_convertvector(v, bf16x2v)); }
; DI void attn_prompt_item(const Params& p, int item, ldsp lds, int tid_) {
;     ...
; #pragma unroll
;       for (int dt = 0; dt < 4; ++dt) { va[dt][0] = *(const LAS u32x2*)VF_ADDR(0, dt, 0); va[dt][1] = *(const LAS u32x2*)VF_ADDR(0, dt, 1); }
; #pragma unroll
;       for (int gi = 0; gi < 16; ++gi) {
;         if (gi + 1 < 16) {
; #pragma unroll
;           for (int dt = 0; dt < 4; ++dt) {
;             if (gi & 1) { va[dt][0] = *(const LAS u32x2*)VF_ADDR(gi + 1, dt, 0); va[dt][1] = *(const LAS u32x2*)VF_ADDR(gi + 1, dt, 1); }
;             else { vb[dt][0] = *(const LAS u32x2*)VF_ADDR(gi + 1, dt, 0); vb[dt][1] = *(const LAS u32x2*)VF_ADDR(gi + 1, dt, 1); } } }
; #pragma unroll
;         for (int dt = 0; dt < 4; ++dt) { const u32x2 lo = (gi & 1) ? vb[dt][0] : va[dt][0], hi = (gi & 1) ? vb[dt][1] : va[dt][1];
;           u32x4 vw; vw.x = lo.x; vw.y = lo.y; vw.z = hi.x; vw.w = hi.y;
;           O[dt] = __builtin_amdgcn_mfma_f32_32x32x16_bf16(__builtin_bit_cast(bf16x8, vw), pb[gi >> 1][gi & 1], O[dt], 0, 0, 0); }
;         __builtin_amdgcn_sched_barrier(0);
;       }
;     ...
;     }
; #pragma unroll
;     for (int dt = 0; dt < 4; ++dt)
; #pragma unroll
;       for (int g4 = 0; g4 < 4; ++g4) { u32x2 w; w.x = pk2(O[dt][4 * g4] * inv, O[dt][4 * g4 + 1] * inv); w.y = pk2(O[dt][4 * g4 + 2] * inv, O[dt][4 * g4 + 3] * inv);
;         *(u32x2*)((bf16_t*)(p.ws + B_XA) + qrow * D + h * 256 + (dh * 4 + dt) * 32 + 8 * g4 + 4 * h2) = w; }
	v_mov_b32_e32 v174, v150
	v_mov_b32_e32 v175, v151
	s_waitcnt lgkmcnt(2)
	v_mov_b32_e32 v176, v154
	v_mov_b32_e32 v177, v155
	v_mov_b32_e32 v154, v152
	v_mov_b32_e32 v155, v153
	s_waitcnt lgkmcnt(1)
	v_mov_b32_e32 v150, v164
	v_mov_b32_e32 v151, v165
	s_waitcnt lgkmcnt(0)
	v_mov_b32_e32 v152, v178
	v_mov_b32_e32 v153, v179
	v_mov_b32_e32 v178, v166
	v_mov_b32_e32 v179, v167
	v_mfma_f32_32x32x16_bf16 v[48:63], v[174:177], v[64:67], v[48:63]
	v_mfma_f32_32x32x16_bf16 v[32:47], v[154:157], v[64:67], v[32:47]
	v_mfma_f32_32x32x16_bf16 v[16:31], v[150:153], v[64:67], v[16:31]
	v_mfma_f32_32x32x16_bf16 v[0:15], v[178:181], v[64:67], v[0:15]
	s_nop 8
	v_lshl_add_u64 v[196:197], s[42:43], 0, v[162:163]
	v_lshl_add_u64 v[196:197], v[196:197], 0, s[26:27]
	v_lshl_add_u64 v[196:197], v[196:197], 0, v[160:161]
	v_add_co_u32_e32 v130, vcc, s38, v196
	v_mbcnt_lo_u32_b32 v198, -1, 0
	v_mbcnt_hi_u32_b32 v198, -1, v198
	v_addc_co_u32_e32 v131, vcc, 0, v197, vcc
	v_and_b32_e32 v198, 32, v198
	v_lshrrev_b32_e32 v198, 2, v198
	v_mov_b32_e32 v199, 0
	v_lshl_add_u64 v[130:131], v[130:131], 0, v[198:199]
	v_pk_mul_f32 v[48:49], v[128:129], v[48:49] op_sel_hi:[0,1]
	v_pk_mul_f32 v[50:51], v[128:129], v[50:51] op_sel_hi:[0,1]
	v_pk_mul_f32 v[52:53], v[128:129], v[52:53] op_sel_hi:[0,1]
	v_pk_mul_f32 v[54:55], v[128:129], v[54:55] op_sel_hi:[0,1]
	v_cvt_pk_bf16_f32 v48, v48, v49
	v_cvt_pk_bf16_f32 v49, v50, v51
	v_cvt_pk_bf16_f32 v50, v52, v53
	v_cvt_pk_bf16_f32 v51, v54, v55
	v_pk_mul_f32 v[32:33], v[128:129], v[32:33] op_sel_hi:[0,1]
	v_pk_mul_f32 v[34:35], v[128:129], v[34:35] op_sel_hi:[0,1]
	v_pk_mul_f32 v[36:37], v[128:129], v[36:37] op_sel_hi:[0,1]
	v_pk_mul_f32 v[38:39], v[128:129], v[38:39] op_sel_hi:[0,1]
	v_cvt_pk_bf16_f32 v32, v32, v33
	v_cvt_pk_bf16_f32 v33, v34, v35
	v_cvt_pk_bf16_f32 v34, v36, v37
	v_cvt_pk_bf16_f32 v35, v38, v39
	v_pk_mul_f32 v[16:17], v[128:129], v[16:17] op_sel_hi:[0,1]
	v_pk_mul_f32 v[18:19], v[128:129], v[18:19] op_sel_hi:[0,1]
	v_pk_mul_f32 v[20:21], v[128:129], v[20:21] op_sel_hi:[0,1]
	v_pk_mul_f32 v[22:23], v[128:129], v[22:23] op_sel_hi:[0,1]
	v_cvt_pk_bf16_f32 v16, v16, v17
	v_cvt_pk_bf16_f32 v17, v18, v19
	v_cvt_pk_bf16_f32 v18, v20, v21
	v_cvt_pk_bf16_f32 v19, v22, v23
	v_pk_mul_f32 v[0:1], v[128:129], v[0:1] op_sel_hi:[0,1]
	v_pk_mul_f32 v[2:3], v[128:129], v[2:3] op_sel_hi:[0,1]
	v_pk_mul_f32 v[4:5], v[128:129], v[4:5] op_sel_hi:[0,1]
	v_pk_mul_f32 v[6:7], v[128:129], v[6:7] op_sel_hi:[0,1]
	v_cvt_pk_bf16_f32 v0, v0, v1
	v_cvt_pk_bf16_f32 v1, v2, v3
	v_cvt_pk_bf16_f32 v2, v4, v5
	v_cvt_pk_bf16_f32 v3, v6, v7
	s_nop 1
	v_permlane32_swap_b32_e32 v48, v50
	v_permlane32_swap_b32_e32 v49, v51
	global_store_dwordx4 v[130:131], v[48:51], off
	v_permlane32_swap_b32_e32 v32, v34
	v_permlane32_swap_b32_e32 v33, v35
	global_store_dwordx4 v[130:131], v[32:35], off offset:64
	v_permlane32_swap_b32_e32 v16, v18
	v_permlane32_swap_b32_e32 v17, v19
	global_store_dwordx4 v[130:131], v[16:19], off offset:128
	v_permlane32_swap_b32_e32 v0, v2
	v_permlane32_swap_b32_e32 v1, v3
	global_store_dwordx4 v[130:131], v[0:3], off offset:192
	v_pk_mul_f32 v[56:57], v[128:129], v[56:57] op_sel_hi:[0,1]
	v_pk_mul_f32 v[58:59], v[128:129], v[58:59] op_sel_hi:[0,1]
	v_pk_mul_f32 v[60:61], v[128:129], v[60:61] op_sel_hi:[0,1]
	v_pk_mul_f32 v[62:63], v[128:129], v[62:63] op_sel_hi:[0,1]
	v_cvt_pk_bf16_f32 v56, v56, v57
	v_cvt_pk_bf16_f32 v57, v58, v59
	v_cvt_pk_bf16_f32 v58, v60, v61
	v_cvt_pk_bf16_f32 v59, v62, v63
	v_pk_mul_f32 v[40:41], v[128:129], v[40:41] op_sel_hi:[0,1]
	v_pk_mul_f32 v[42:43], v[128:129], v[42:43] op_sel_hi:[0,1]
	v_pk_mul_f32 v[44:45], v[128:129], v[44:45] op_sel_hi:[0,1]
	v_pk_mul_f32 v[46:47], v[128:129], v[46:47] op_sel_hi:[0,1]
	v_cvt_pk_bf16_f32 v40, v40, v41
	v_cvt_pk_bf16_f32 v41, v42, v43
	v_cvt_pk_bf16_f32 v42, v44, v45
	v_cvt_pk_bf16_f32 v43, v46, v47
	v_pk_mul_f32 v[24:25], v[128:129], v[24:25] op_sel_hi:[0,1]
	v_pk_mul_f32 v[26:27], v[128:129], v[26:27] op_sel_hi:[0,1]
	v_pk_mul_f32 v[28:29], v[128:129], v[28:29] op_sel_hi:[0,1]
	v_pk_mul_f32 v[30:31], v[128:129], v[30:31] op_sel_hi:[0,1]
	v_cvt_pk_bf16_f32 v24, v24, v25
	v_cvt_pk_bf16_f32 v25, v26, v27
	v_cvt_pk_bf16_f32 v26, v28, v29
	v_cvt_pk_bf16_f32 v27, v30, v31
	v_pk_mul_f32 v[8:9], v[128:129], v[8:9] op_sel_hi:[0,1]
	v_pk_mul_f32 v[10:11], v[128:129], v[10:11] op_sel_hi:[0,1]
	v_pk_mul_f32 v[12:13], v[128:129], v[12:13] op_sel_hi:[0,1]
	v_pk_mul_f32 v[14:15], v[128:129], v[14:15] op_sel_hi:[0,1]
	v_cvt_pk_bf16_f32 v8, v8, v9
	v_cvt_pk_bf16_f32 v9, v10, v11
	v_cvt_pk_bf16_f32 v10, v12, v13
	v_cvt_pk_bf16_f32 v11, v14, v15
	s_nop 1
	v_permlane32_swap_b32_e32 v56, v58
	v_permlane32_swap_b32_e32 v57, v59
	global_store_dwordx4 v[130:131], v[56:59], off offset:32
	v_permlane32_swap_b32_e32 v40, v42
	v_permlane32_swap_b32_e32 v41, v43
	global_store_dwordx4 v[130:131], v[40:43], off offset:96
	v_permlane32_swap_b32_e32 v24, v26
	v_permlane32_swap_b32_e32 v25, v27
	global_store_dwordx4 v[130:131], v[24:27], off offset:160
	v_permlane32_swap_b32_e32 v8, v10
	v_permlane32_swap_b32_e32 v9, v11
	global_store_dwordx4 v[130:131], v[8:11], off offset:224
	v_add_u32_e32 v158, s39, v172
	v_add3_u32 v0, v158, v146, v160
	v_add3_u32 v2, v158, v139, v160
	ds_read_b64 v[0:1], v0
	ds_read_b64 v[2:3], v2
	v_add_u32_e32 v159, s40, v172
	v_add_u32_e32 v166, s41, v172
	v_add_u32_e32 v167, s44, v172
	v_add3_u32 v4, v159, v146, v160
	v_add3_u32 v6, v159, v139, v160
	v_add3_u32 v8, v166, v146, v160
	v_add3_u32 v9, v166, v139, v160
	v_add3_u32 v10, v167, v146, v160
	v_add3_u32 v11, v167, v139, v160
	v_add3_u32 v139, v158, v147, v160
	v_add3_u32 v175, v166, v147, v160
	ds_read_b64 v[4:5], v4
	ds_read_b64 v[6:7], v6
	s_waitcnt lgkmcnt(2)
; #define LAS __attribute__((address_space(3)))
; DI void attn_prompt_item(const Params& p, int item, ldsp lds, int tid_) {
;     ...
;     {
;       u32x2 va[4][2], vb[4][2];
;     ...
; #pragma unroll
;       for (int dt = 0; dt < 4; ++dt) { va[dt][0] = *(const LAS u32x2*)VF_ADDR(0, dt, 0); va[dt][1] = *(const LAS u32x2*)VF_ADDR(0, dt, 1); }
; #pragma unroll
;       for (int gi = 0; gi < 16; ++gi) {
;         if (gi + 1 < 16) {
; #pragma unroll
;           for (int dt = 0; dt < 4; ++dt) {
;             if (gi & 1) { va[dt][0] = *(const LAS u32x2*)VF_ADDR(gi + 1, dt, 0); va[dt][1] = *(const LAS u32x2*)VF_ADDR(gi + 1, dt, 1); }
;             else { vb[dt][0] = *(const LAS u32x2*)VF_ADDR(gi + 1, dt, 0); vb[dt][1] = *(const LAS u32x2*)VF_ADDR(gi + 1, dt, 1); } } }
; #pragma unroll
;         for (int dt = 0; dt < 4; ++dt) { const u32x2 lo = (gi & 1) ? vb[dt][0] : va[dt][0], hi = (gi & 1) ? vb[dt][1] : va[dt][1];
;           u32x4 vw; vw.x = lo.x; vw.y = lo.y; vw.z = hi.x; vw.w = hi.y;
;           O[dt] = __builtin_amdgcn_mfma_f32_32x32x16_bf16(__builtin_bit_cast(bf16x8, vw), pb[gi >> 1][gi & 1], O[dt], 0, 0, 0); }
;         __builtin_amdgcn_sched_barrier(0);
;       }
	v_mfma_f32_32x32x16_bf16 v[48:63], v[0:3], v[108:111], 0
	ds_read_b64 v[0:1], v8
	ds_read_b64 v[2:3], v9
	ds_read_b64 v[8:9], v10
	ds_read_b64 v[10:11], v11
	v_add3_u32 v172, v158, v148, v160
	v_add3_u32 v173, v159, v147, v160
	v_add3_u32 v174, v159, v148, v160
	ds_read_b64 v[150:151], v139
	ds_read_b64 v[152:153], v172
	ds_read_b64 v[154:155], v173
	ds_read_b64 v[156:157], v174
	v_add3_u32 v176, v166, v148, v160
	v_add3_u32 v177, v167, v147, v160
	v_add3_u32 v178, v167, v148, v160
	ds_read_b64 v[146:147], v175
	ds_read_b64 v[148:149], v176
	ds_read_b64 v[162:163], v177
	ds_read_b64 v[164:165], v178
	s_waitcnt lgkmcnt(12)
	v_mfma_f32_32x32x16_bf16 v[32:47], v[4:7], v[108:111], 0
	s_waitcnt lgkmcnt(10)
	v_mfma_f32_32x32x16_bf16 v[16:31], v[0:3], v[108:111], 0
	s_waitcnt lgkmcnt(8)
	v_mfma_f32_32x32x16_bf16 v[0:15], v[8:11], v[108:111], 0
	v_add3_u32 v179, v158, v144, v160
	v_add3_u32 v183, v166, v144, v160
	s_waitcnt lgkmcnt(6)
	v_mfma_f32_32x32x16_bf16 v[48:63], v[150:153], v[124:127], v[48:63]
	v_add3_u32 v180, v158, v145, v160
	v_add3_u32 v181, v159, v144, v160
	v_add3_u32 v182, v159, v145, v160
	ds_read_b64 v[108:109], v179
	ds_read_b64 v[110:111], v180
	ds_read_b64 v[150:151], v181
	ds_read_b64 v[152:153], v182
	v_add3_u32 v184, v166, v145, v160
	v_add3_u32 v185, v167, v144, v160
	v_add3_u32 v186, v167, v145, v160
	s_waitcnt lgkmcnt(8)
	v_mfma_f32_32x32x16_bf16 v[32:47], v[154:157], v[124:127], v[32:47]
	s_waitcnt lgkmcnt(6)
	v_mfma_f32_32x32x16_bf16 v[16:31], v[146:149], v[124:127], v[16:31]
	ds_read_b64 v[144:145], v183
	ds_read_b64 v[146:147], v184
	ds_read_b64 v[154:155], v185
	ds_read_b64 v[156:157], v186
	s_waitcnt lgkmcnt(8)
	v_mfma_f32_32x32x16_bf16 v[0:15], v[162:165], v[124:127], v[0:15]
	v_add3_u32 v162, v158, v142, v160
	s_waitcnt lgkmcnt(4)
	v_mfma_f32_32x32x16_bf16 v[32:47], v[150:153], v[120:123], v[32:47]
	v_add3_u32 v152, v166, v142, v160
	v_add3_u32 v163, v158, v143, v160
	v_add3_u32 v150, v159, v142, v160
	v_add3_u32 v151, v159, v143, v160
	v_add3_u32 v153, v166, v143, v160
	v_add3_u32 v164, v167, v142, v160
	v_add3_u32 v165, v167, v143, v160
	v_mfma_f32_32x32x16_bf16 v[48:63], v[108:111], v[120:123], v[48:63]
	ds_read_b64 v[108:109], v162
	ds_read_b64 v[110:111], v163
	ds_read_b64 v[124:125], v150
	ds_read_b64 v[126:127], v151
	s_waitcnt lgkmcnt(6)
	v_mfma_f32_32x32x16_bf16 v[16:31], v[144:147], v[120:123], v[16:31]
	ds_read_b64 v[142:143], v152
	ds_read_b64 v[144:145], v153
	ds_read_b64 v[146:147], v164
	ds_read_b64 v[148:149], v165
	s_waitcnt lgkmcnt(8)
	v_mfma_f32_32x32x16_bf16 v[0:15], v[154:157], v[120:123], v[0:15]
	v_add3_u32 v154, v158, v140, v160
	v_add3_u32 v187, v166, v140, v160
	s_waitcnt lgkmcnt(6)
	v_mfma_f32_32x32x16_bf16 v[48:63], v[108:111], v[116:119], v[48:63]
	v_add3_u32 v155, v158, v141, v160
	v_add3_u32 v156, v159, v140, v160
	v_add3_u32 v157, v159, v141, v160
	ds_read_b64 v[108:109], v154
	ds_read_b64 v[110:111], v155
	ds_read_b64 v[120:121], v156
	ds_read_b64 v[122:123], v157
	v_add3_u32 v188, v167, v141, v160
	s_waitcnt lgkmcnt(8)
	v_mfma_f32_32x32x16_bf16 v[32:47], v[124:127], v[116:119], v[32:47]
	s_waitcnt lgkmcnt(6)
	v_mfma_f32_32x32x16_bf16 v[16:31], v[142:145], v[116:119], v[16:31]
	v_add3_u32 v144, v166, v141, v160
	v_add3_u32 v145, v167, v140, v160
	ds_read_b64 v[124:125], v187
	ds_read_b64 v[126:127], v144
	ds_read_b64 v[140:141], v145
	ds_read_b64 v[142:143], v188
	s_waitcnt lgkmcnt(8)
	v_mfma_f32_32x32x16_bf16 v[0:15], v[146:149], v[116:119], v[0:15]
	v_add3_u32 v146, v158, v137, v160
	v_add3_u32 v189, v166, v137, v160
	s_waitcnt lgkmcnt(6)
	v_mfma_f32_32x32x16_bf16 v[48:63], v[108:111], v[112:115], v[48:63]
	v_add3_u32 v147, v158, v138, v160
	v_add3_u32 v148, v159, v137, v160
	v_add3_u32 v149, v159, v138, v160
	ds_read_b64 v[108:109], v146
	ds_read_b64 v[110:111], v147
	ds_read_b64 v[116:117], v148
	ds_read_b64 v[118:119], v149
	v_add3_u32 v190, v166, v138, v160
	v_add3_u32 v137, v167, v137, v160
	v_add3_u32 v138, v167, v138, v160
	s_waitcnt lgkmcnt(8)
	v_mfma_f32_32x32x16_bf16 v[32:47], v[120:123], v[112:115], v[32:47]
	s_waitcnt lgkmcnt(6)
	v_mfma_f32_32x32x16_bf16 v[16:31], v[124:127], v[112:115], v[16:31]
	ds_read_b64 v[120:121], v189
	ds_read_b64 v[122:123], v190
	ds_read_b64 v[124:125], v137
	ds_read_b64 v[126:127], v138
	s_waitcnt lgkmcnt(8)
	v_mfma_f32_32x32x16_bf16 v[0:15], v[140:143], v[112:115], v[0:15]
	v_add3_u32 v140, v158, v135, v160
	v_add3_u32 v191, v166, v135, v160
	s_waitcnt lgkmcnt(6)
	v_mfma_f32_32x32x16_bf16 v[48:63], v[108:111], v[104:107], v[48:63]
	v_add3_u32 v141, v158, v136, v160
	v_add3_u32 v142, v159, v135, v160
	v_add3_u32 v143, v159, v136, v160
	ds_read_b64 v[108:109], v140
	ds_read_b64 v[110:111], v141
	ds_read_b64 v[112:113], v142
	ds_read_b64 v[114:115], v143
	v_add3_u32 v192, v166, v136, v160
	v_add3_u32 v135, v167, v135, v160
	v_add3_u32 v136, v167, v136, v160
	s_waitcnt lgkmcnt(8)
	v_mfma_f32_32x32x16_bf16 v[32:47], v[116:119], v[104:107], v[32:47]
	s_waitcnt lgkmcnt(6)
	v_mfma_f32_32x32x16_bf16 v[16:31], v[120:123], v[104:107], v[16:31]
	ds_read_b64 v[116:117], v191
	ds_read_b64 v[118:119], v192
	ds_read_b64 v[120:121], v135
	ds_read_b64 v[122:123], v136
	s_waitcnt lgkmcnt(8)
	v_mfma_f32_32x32x16_bf16 v[0:15], v[124:127], v[104:107], v[0:15]
	v_add3_u32 v124, v158, v133, v160
	v_add3_u32 v193, v166, v133, v160
	s_waitcnt lgkmcnt(6)
	v_mfma_f32_32x32x16_bf16 v[48:63], v[108:111], v[100:103], v[48:63]
	v_add3_u32 v125, v158, v134, v160
	v_add3_u32 v126, v159, v133, v160
	v_add3_u32 v127, v159, v134, v160
	ds_read_b64 v[104:105], v124
	ds_read_b64 v[106:107], v125
	ds_read_b64 v[108:109], v126
	ds_read_b64 v[110:111], v127
	v_add3_u32 v194, v166, v134, v160
	v_add3_u32 v133, v167, v133, v160
	v_add3_u32 v134, v167, v134, v160
	s_waitcnt lgkmcnt(8)
; #define LAS __attribute__((address_space(3)))
; DI void attn_prompt_item(const Params& p, int item, ldsp lds, int tid_) {
;     ...
;       for (int gi = 0; gi < 16; ++gi) {
;         if (gi + 1 < 16) {
; #pragma unroll
;           for (int dt = 0; dt < 4; ++dt) {
;             if (gi & 1) { va[dt][0] = *(const LAS u32x2*)VF_ADDR(gi + 1, dt, 0); va[dt][1] = *(const LAS u32x2*)VF_ADDR(gi + 1, dt, 1); }
;             else { vb[dt][0] = *(const LAS u32x2*)VF_ADDR(gi + 1, dt, 0); vb[dt][1] = *(const LAS u32x2*)VF_ADDR(gi + 1, dt, 1); } } }
; #pragma unroll
;         for (int dt = 0; dt < 4; ++dt) { const u32x2 lo = (gi & 1) ? vb[dt][0] : va[dt][0], hi = (gi & 1) ? vb[dt][1] : va[dt][1];
;           u32x4 vw; vw.x = lo.x; vw.y = lo.y; vw.z = hi.x; vw.w = hi.y;
;           O[dt] = __builtin_amdgcn_mfma_f32_32x32x16_bf16(__builtin_bit_cast(bf16x8, vw), pb[gi >> 1][gi & 1], O[dt], 0, 0, 0); }
;         __builtin_amdgcn_sched_barrier(0);
;       }
	v_mfma_f32_32x32x16_bf16 v[32:47], v[112:115], v[100:103], v[32:47]
	s_waitcnt lgkmcnt(6)
	v_mfma_f32_32x32x16_bf16 v[16:31], v[116:119], v[100:103], v[16:31]
	ds_read_b64 v[112:113], v193
	ds_read_b64 v[114:115], v194
	ds_read_b64 v[116:117], v133
	ds_read_b64 v[118:119], v134
	s_waitcnt lgkmcnt(8)
	v_mfma_f32_32x32x16_bf16 v[0:15], v[120:123], v[100:103], v[0:15]
	s_waitcnt lgkmcnt(6)
	v_mfma_f32_32x32x16_bf16 v[48:63], v[104:107], v[96:99], v[48:63]
	v_add3_u32 v100, v158, v129, v160
	v_add3_u32 v102, v158, v132, v160
	v_add3_u32 v104, v159, v129, v160
	v_add3_u32 v106, v159, v132, v160
	ds_read_b64 v[100:101], v100 offset:256
	ds_read_b64 v[102:103], v102 offset:256
	ds_read_b64 v[104:105], v104 offset:256
	ds_read_b64 v[106:107], v106 offset:256
	s_waitcnt lgkmcnt(8)
	v_mfma_f32_32x32x16_bf16 v[32:47], v[108:111], v[96:99], v[32:47]
	v_add3_u32 v108, v166, v129, v160
	v_add3_u32 v110, v166, v132, v160
	s_waitcnt lgkmcnt(6)
	v_mfma_f32_32x32x16_bf16 v[16:31], v[112:115], v[96:99], v[16:31]
	v_add3_u32 v112, v167, v129, v160
	v_add3_u32 v114, v167, v132, v160
	ds_read_b64 v[108:109], v108 offset:256
	ds_read_b64 v[110:111], v110 offset:256
	ds_read_b64 v[112:113], v112 offset:256
	ds_read_b64 v[114:115], v114 offset:256
	s_waitcnt lgkmcnt(8)
	v_mfma_f32_32x32x16_bf16 v[0:15], v[116:119], v[96:99], v[0:15]
	s_waitcnt lgkmcnt(6)
	v_mfma_f32_32x32x16_bf16 v[48:63], v[100:103], v[92:95], v[48:63]
	s_waitcnt lgkmcnt(4)
	v_mfma_f32_32x32x16_bf16 v[32:47], v[104:107], v[92:95], v[32:47]
	s_waitcnt lgkmcnt(2)
	v_mfma_f32_32x32x16_bf16 v[16:31], v[108:111], v[92:95], v[16:31]
	ds_read_b64 v[96:97], v139 offset:256
	ds_read_b64 v[98:99], v172 offset:256
	ds_read_b64 v[100:101], v173 offset:256
	ds_read_b64 v[102:103], v174 offset:256
	ds_read_b64 v[104:105], v175 offset:256
	ds_read_b64 v[106:107], v176 offset:256
	ds_read_b64 v[108:109], v177 offset:256
	ds_read_b64 v[110:111], v178 offset:256
	s_waitcnt lgkmcnt(8)
	v_mfma_f32_32x32x16_bf16 v[0:15], v[112:115], v[92:95], v[0:15]
	s_waitcnt lgkmcnt(6)
	v_mfma_f32_32x32x16_bf16 v[48:63], v[96:99], v[88:91], v[48:63]
	s_waitcnt lgkmcnt(4)
	v_mfma_f32_32x32x16_bf16 v[32:47], v[100:103], v[88:91], v[32:47]
	s_waitcnt lgkmcnt(2)
	v_mfma_f32_32x32x16_bf16 v[16:31], v[104:107], v[88:91], v[16:31]
	ds_read_b64 v[92:93], v179 offset:256
	ds_read_b64 v[94:95], v180 offset:256
	ds_read_b64 v[96:97], v181 offset:256
	ds_read_b64 v[98:99], v182 offset:256
	ds_read_b64 v[100:101], v183 offset:256
	ds_read_b64 v[102:103], v184 offset:256
	ds_read_b64 v[104:105], v185 offset:256
	ds_read_b64 v[106:107], v186 offset:256
	s_waitcnt lgkmcnt(8)
	v_mfma_f32_32x32x16_bf16 v[0:15], v[108:111], v[88:91], v[0:15]
	s_waitcnt lgkmcnt(6)
	v_mfma_f32_32x32x16_bf16 v[48:63], v[92:95], v[84:87], v[48:63]
	s_waitcnt lgkmcnt(4)
	v_mfma_f32_32x32x16_bf16 v[32:47], v[96:99], v[84:87], v[32:47]
	s_waitcnt lgkmcnt(2)
	v_mfma_f32_32x32x16_bf16 v[16:31], v[100:103], v[84:87], v[16:31]
	ds_read_b64 v[88:89], v162 offset:256
	ds_read_b64 v[90:91], v163 offset:256
	ds_read_b64 v[92:93], v150 offset:256
	ds_read_b64 v[94:95], v151 offset:256
	ds_read_b64 v[96:97], v152 offset:256
	ds_read_b64 v[98:99], v153 offset:256
	ds_read_b64 v[100:101], v164 offset:256
	ds_read_b64 v[102:103], v165 offset:256
	s_waitcnt lgkmcnt(8)
	v_mfma_f32_32x32x16_bf16 v[0:15], v[104:107], v[84:87], v[0:15]
	s_waitcnt lgkmcnt(6)
	v_mfma_f32_32x32x16_bf16 v[48:63], v[88:91], v[80:83], v[48:63]
	s_waitcnt lgkmcnt(4)
	v_mfma_f32_32x32x16_bf16 v[32:47], v[92:95], v[80:83], v[32:47]
	s_waitcnt lgkmcnt(2)
	v_mfma_f32_32x32x16_bf16 v[16:31], v[96:99], v[80:83], v[16:31]
	ds_read_b64 v[84:85], v154 offset:256
	ds_read_b64 v[86:87], v155 offset:256
	ds_read_b64 v[88:89], v156 offset:256
	ds_read_b64 v[90:91], v157 offset:256
	ds_read_b64 v[92:93], v187 offset:256
	ds_read_b64 v[94:95], v144 offset:256
	ds_read_b64 v[96:97], v145 offset:256
	ds_read_b64 v[98:99], v188 offset:256
	s_waitcnt lgkmcnt(8)
	v_mfma_f32_32x32x16_bf16 v[0:15], v[100:103], v[80:83], v[0:15]
	s_waitcnt lgkmcnt(6)
	v_mfma_f32_32x32x16_bf16 v[48:63], v[84:87], v[76:79], v[48:63]
	s_waitcnt lgkmcnt(4)
	v_mfma_f32_32x32x16_bf16 v[32:47], v[88:91], v[76:79], v[32:47]
	s_waitcnt lgkmcnt(2)
	v_mfma_f32_32x32x16_bf16 v[16:31], v[92:95], v[76:79], v[16:31]
	ds_read_b64 v[80:81], v146 offset:256
	ds_read_b64 v[82:83], v147 offset:256
	ds_read_b64 v[84:85], v148 offset:256
	ds_read_b64 v[86:87], v149 offset:256
	ds_read_b64 v[88:89], v189 offset:256
	ds_read_b64 v[90:91], v190 offset:256
	ds_read_b64 v[92:93], v137 offset:256
	ds_read_b64 v[94:95], v138 offset:256
	s_waitcnt lgkmcnt(8)
	v_mfma_f32_32x32x16_bf16 v[0:15], v[96:99], v[76:79], v[0:15]
	s_waitcnt lgkmcnt(6)
	v_mfma_f32_32x32x16_bf16 v[48:63], v[80:83], v[72:75], v[48:63]
	s_waitcnt lgkmcnt(4)
	v_mfma_f32_32x32x16_bf16 v[32:47], v[84:87], v[72:75], v[32:47]
	s_waitcnt lgkmcnt(2)
	v_mfma_f32_32x32x16_bf16 v[16:31], v[88:91], v[72:75], v[16:31]
	ds_read_b64 v[76:77], v140 offset:256
	ds_read_b64 v[78:79], v141 offset:256
	ds_read_b64 v[80:81], v142 offset:256
	ds_read_b64 v[82:83], v143 offset:256
	ds_read_b64 v[84:85], v191 offset:256
	ds_read_b64 v[86:87], v192 offset:256
	ds_read_b64 v[88:89], v135 offset:256
	ds_read_b64 v[90:91], v136 offset:256
	s_waitcnt lgkmcnt(8)
	v_mfma_f32_32x32x16_bf16 v[0:15], v[92:95], v[72:75], v[0:15]
	s_waitcnt lgkmcnt(6)
	v_mfma_f32_32x32x16_bf16 v[48:63], v[76:79], v[68:71], v[48:63]
	s_waitcnt lgkmcnt(4)
	v_mfma_f32_32x32x16_bf16 v[32:47], v[80:83], v[68:71], v[32:47]
	s_waitcnt lgkmcnt(2)
; DI unsigned pk2(float lo, float hi) { f32x2 v = {lo, hi}; return __builtin_bit_cast(unsigned, __builtin_convertvector(v, bf16x2v)); }
; DI void attn_prompt_item(const Params& p, int item, ldsp lds, int tid_) {
;     ...
;         for (int dt = 0; dt < 4; ++dt) { const u32x2 lo = (gi & 1) ? vb[dt][0] : va[dt][0], hi = (gi & 1) ? vb[dt][1] : va[dt][1];
;           u32x4 vw; vw.x = lo.x; vw.y = lo.y; vw.z = hi.x; vw.w = hi.y;
;           O[dt] = __builtin_amdgcn_mfma_f32_32x32x16_bf16(__builtin_bit_cast(bf16x8, vw), pb[gi >> 1][gi & 1], O[dt], 0, 0, 0); }
;         __builtin_amdgcn_sched_barrier(0);
;       }
;     ...
;     }
; #pragma unroll
;     for (int dt = 0; dt < 4; ++dt)
; #pragma unroll
;       for (int g4 = 0; g4 < 4; ++g4) { u32x2 w; w.x = pk2(O[dt][4 * g4] * inv, O[dt][4 * g4 + 1] * inv); w.y = pk2(O[dt][4 * g4 + 2] * inv, O[dt][4 * g4 + 3] * inv);
;         *(u32x2*)((bf16_t*)(p.ws + B_XA) + qrow * D + h * 256 + (dh * 4 + dt) * 32 + 8 * g4 + 4 * h2) = w; }
;   }
;   __syncthreads();
; DI void phase_attn(const Params& p, ldsp lds, int tid) {
;   const int G = gridDim.x;
;   if (blockIdx.x & 1) for (int j = blockIdx.x; j < 512; j += G) attn_sample_item(p, j, lds, tid);
;   for (int i = blockIdx.x; i < 256; i += G) attn_prompt_item(p, i, lds, tid);
;   if (!(blockIdx.x & 1)) for (int j = blockIdx.x; j < 512; j += G) attn_sample_item(p, j, lds, tid);
; }
	v_mfma_f32_32x32x16_bf16 v[16:31], v[84:87], v[68:71], v[16:31]
	ds_read_b64 v[72:73], v124 offset:256
	ds_read_b64 v[74:75], v125 offset:256
	ds_read_b64 v[76:77], v126 offset:256
	ds_read_b64 v[78:79], v127 offset:256
	ds_read_b64 v[80:81], v193 offset:256
	ds_read_b64 v[82:83], v194 offset:256
	ds_read_b64 v[84:85], v133 offset:256
	ds_read_b64 v[86:87], v134 offset:256
	s_waitcnt lgkmcnt(8)
	v_mfma_f32_32x32x16_bf16 v[0:15], v[88:91], v[68:71], v[0:15]
	s_waitcnt lgkmcnt(6)
	v_mfma_f32_32x32x16_bf16 v[48:63], v[72:75], v[64:67], v[48:63]
	s_waitcnt lgkmcnt(4)
	v_mfma_f32_32x32x16_bf16 v[32:47], v[76:79], v[64:67], v[32:47]
	s_waitcnt lgkmcnt(2)
	v_mfma_f32_32x32x16_bf16 v[16:31], v[80:83], v[64:67], v[16:31]
	s_waitcnt lgkmcnt(0)
	v_mfma_f32_32x32x16_bf16 v[0:15], v[84:87], v[64:67], v[0:15]
	s_nop 5
	v_pk_mul_f32 v[48:49], v[128:129], v[48:49] op_sel_hi:[0,1]
	v_pk_mul_f32 v[50:51], v[128:129], v[50:51] op_sel_hi:[0,1]
	v_pk_mul_f32 v[52:53], v[128:129], v[52:53] op_sel_hi:[0,1]
	v_pk_mul_f32 v[54:55], v[128:129], v[54:55] op_sel_hi:[0,1]
	v_cvt_pk_bf16_f32 v48, v48, v49
	v_cvt_pk_bf16_f32 v49, v50, v51
	v_cvt_pk_bf16_f32 v50, v52, v53
	v_cvt_pk_bf16_f32 v51, v54, v55
	v_pk_mul_f32 v[32:33], v[128:129], v[32:33] op_sel_hi:[0,1]
	v_pk_mul_f32 v[34:35], v[128:129], v[34:35] op_sel_hi:[0,1]
	v_pk_mul_f32 v[36:37], v[128:129], v[36:37] op_sel_hi:[0,1]
	v_pk_mul_f32 v[38:39], v[128:129], v[38:39] op_sel_hi:[0,1]
	v_cvt_pk_bf16_f32 v32, v32, v33
	v_cvt_pk_bf16_f32 v33, v34, v35
	v_cvt_pk_bf16_f32 v34, v36, v37
	v_cvt_pk_bf16_f32 v35, v38, v39
	v_pk_mul_f32 v[16:17], v[128:129], v[16:17] op_sel_hi:[0,1]
	v_pk_mul_f32 v[18:19], v[128:129], v[18:19] op_sel_hi:[0,1]
	v_pk_mul_f32 v[20:21], v[128:129], v[20:21] op_sel_hi:[0,1]
	v_pk_mul_f32 v[22:23], v[128:129], v[22:23] op_sel_hi:[0,1]
	v_cvt_pk_bf16_f32 v16, v16, v17
	v_cvt_pk_bf16_f32 v17, v18, v19
	v_cvt_pk_bf16_f32 v18, v20, v21
	v_cvt_pk_bf16_f32 v19, v22, v23
	v_pk_mul_f32 v[0:1], v[128:129], v[0:1] op_sel_hi:[0,1]
	v_pk_mul_f32 v[2:3], v[128:129], v[2:3] op_sel_hi:[0,1]
	v_pk_mul_f32 v[4:5], v[128:129], v[4:5] op_sel_hi:[0,1]
	v_pk_mul_f32 v[6:7], v[128:129], v[6:7] op_sel_hi:[0,1]
	v_cvt_pk_bf16_f32 v0, v0, v1
	v_cvt_pk_bf16_f32 v1, v2, v3
	v_cvt_pk_bf16_f32 v2, v4, v5
	v_cvt_pk_bf16_f32 v3, v6, v7
	s_nop 1
	v_permlane32_swap_b32_e32 v48, v50
	v_permlane32_swap_b32_e32 v49, v51
	global_store_dwordx4 v[130:131], v[48:51], off offset:256
	v_permlane32_swap_b32_e32 v32, v34
	v_permlane32_swap_b32_e32 v33, v35
	global_store_dwordx4 v[130:131], v[32:35], off offset:320
	v_permlane32_swap_b32_e32 v16, v18
	v_permlane32_swap_b32_e32 v17, v19
	global_store_dwordx4 v[130:131], v[16:19], off offset:384
	v_permlane32_swap_b32_e32 v0, v2
	v_permlane32_swap_b32_e32 v1, v3
	global_store_dwordx4 v[130:131], v[0:3], off offset:448
	v_pk_mul_f32 v[56:57], v[128:129], v[56:57] op_sel_hi:[0,1]
	v_pk_mul_f32 v[58:59], v[128:129], v[58:59] op_sel_hi:[0,1]
	v_pk_mul_f32 v[60:61], v[128:129], v[60:61] op_sel_hi:[0,1]
	v_pk_mul_f32 v[62:63], v[128:129], v[62:63] op_sel_hi:[0,1]
	v_cvt_pk_bf16_f32 v56, v56, v57
	v_cvt_pk_bf16_f32 v57, v58, v59
	v_cvt_pk_bf16_f32 v58, v60, v61
	v_cvt_pk_bf16_f32 v59, v62, v63
	v_pk_mul_f32 v[40:41], v[128:129], v[40:41] op_sel_hi:[0,1]
	v_pk_mul_f32 v[42:43], v[128:129], v[42:43] op_sel_hi:[0,1]
	v_pk_mul_f32 v[44:45], v[128:129], v[44:45] op_sel_hi:[0,1]
	v_pk_mul_f32 v[46:47], v[128:129], v[46:47] op_sel_hi:[0,1]
	v_cvt_pk_bf16_f32 v40, v40, v41
	v_cvt_pk_bf16_f32 v41, v42, v43
	v_cvt_pk_bf16_f32 v42, v44, v45
	v_cvt_pk_bf16_f32 v43, v46, v47
	v_pk_mul_f32 v[24:25], v[128:129], v[24:25] op_sel_hi:[0,1]
	v_pk_mul_f32 v[26:27], v[128:129], v[26:27] op_sel_hi:[0,1]
	v_pk_mul_f32 v[28:29], v[128:129], v[28:29] op_sel_hi:[0,1]
	v_pk_mul_f32 v[30:31], v[128:129], v[30:31] op_sel_hi:[0,1]
	v_cvt_pk_bf16_f32 v24, v24, v25
	v_cvt_pk_bf16_f32 v25, v26, v27
	v_cvt_pk_bf16_f32 v26, v28, v29
	v_cvt_pk_bf16_f32 v27, v30, v31
	v_pk_mul_f32 v[8:9], v[128:129], v[8:9] op_sel_hi:[0,1]
	v_pk_mul_f32 v[10:11], v[128:129], v[10:11] op_sel_hi:[0,1]
	v_pk_mul_f32 v[12:13], v[128:129], v[12:13] op_sel_hi:[0,1]
	v_pk_mul_f32 v[14:15], v[128:129], v[14:15] op_sel_hi:[0,1]
	v_cvt_pk_bf16_f32 v8, v8, v9
	v_cvt_pk_bf16_f32 v9, v10, v11
	v_cvt_pk_bf16_f32 v10, v12, v13
	v_cvt_pk_bf16_f32 v11, v14, v15
	s_nop 1
	s_add_i32 s45, s45, s94
	s_add_i32 s30, s30, s31
	s_add_i32 s33, s33, s34
	s_cmpk_gt_i32 s45, 0xff
	v_permlane32_swap_b32_e32 v56, v58
	v_permlane32_swap_b32_e32 v57, v59
	global_store_dwordx4 v[130:131], v[56:59], off offset:288
	v_permlane32_swap_b32_e32 v40, v42
	v_permlane32_swap_b32_e32 v41, v43
	global_store_dwordx4 v[130:131], v[40:43], off offset:352
	v_permlane32_swap_b32_e32 v24, v26
	v_permlane32_swap_b32_e32 v25, v27
	global_store_dwordx4 v[130:131], v[24:27], off offset:416
	v_permlane32_swap_b32_e32 v8, v10
	v_permlane32_swap_b32_e32 v9, v11
	global_store_dwordx4 v[130:131], v[8:11], off offset:480
	s_barrier
	s_cbranch_scc0 .LBB0_1672
.LBB0_1673:
	s_setprio 0
	s_cmpk_gt_i32 s2, 0x1ff
	s_cselect_b64 s[0:1], -1, 0
	s_xor_b64 s[4:5], s[24:25], -1
	s_or_b64 s[0:1], s[0:1], s[4:5]
	s_and_b64 vcc, exec, s[0:1]
	s_cbranch_vccnz .LBB0_1742
	v_mbcnt_hi_u32_b32 v214, -1, v213
	v_and_b32_e32 v0, 64, v214
	s_lshl_b32 s0, s2, 8
	s_lshl_b32 s1, s94, 8
	s_mov_b32 s25, 0
	v_mov_b32_e32 v145, 0
	s_mov_b32 s3, 0x200000
	s_mov_b32 s33, 0x400000
	s_mov_b32 s34, 0x600000
	v_xor_b32_e32 v215, 1, v214
	v_add_u32_e32 v216, 64, v0
	v_xor_b32_e32 v217, 2, v214
	v_xor_b32_e32 v218, 4, v214
	v_xor_b32_e32 v219, 8, v214
	v_xor_b32_e32 v220, 16, v214
	v_xor_b32_e32 v221, 32, v214
	s_mov_b32 s35, 0xf149f2ca
	s_mov_b32 s38, s2
	s_branch .LBB0_1676
